# adds: rope epilogue duplicate-load elimination, idx score loop counted waits (K tile loads keep one trip in flight), next idx unit's first two key tiles requested before the selection
# speedup vs baseline: 1.0040x; 1.0040x over previous
; __device__ __forceinline__ unsigned cvt_pk_bf16(float lo, float hi) { unsigned r; asm volatile("v_cvt_pk_bf16_f32 %0, %1, %2" : "=v"(r) : "v"(lo), "v"(hi)); return r; }
; template <class V> __device__ __forceinline__ void st_wt16(void* p, const V v) { static_assert(sizeof(V) == 16, "16-byte value"); asm volatile("global_store_dwordx4 %0, %1, off sc1\n\ts_nop 1" ::"v"(p), "v"(v) : "memory"); }
; template <class V> __device__ __forceinline__ void st_wt8(void* p, const V v) { static_assert(sizeof(V) == 8, "8-byte value"); *(V*)p = v; }
; #define EPIIN_LOOP(...) _Pragma("unroll") for (int ai = 0; ai < 2; ++ai) _Pragma("unroll") for (int m = 0; m < 4; ++m) { const int row = row0 + ai * HALF + m * 16, t = row & (seq - 1); (void)t; \
;         _Pragma("unroll") for (int bj = 0; bj < 2; ++bj) { const int within = bj * HALF + wc * 32 + 8 * fq; const f32x4 v0 = acc[ai][bj][m][0], v1 = acc[ai][bj][m][1]; __VA_ARGS__ } }
;     __device__ __forceinline__ void operator()(const f32x4 (&acc)[2][2][4][2], const Unit& u, int wr, int wc, int fr, int fq) const {
;     ...
;         } else if (pn == 9) {
;             EPIIN_LOOP({ const int hd = within >> 6, d = ((within & 63) >> 3) * 4; const f32x4 cc = *(const f32x4*)(rc + (size_t)t * 32 + d), ss = *(const f32x4*)(rs + (size_t)t * 32 + d);
;                 const f32x4 o1 = v0 * cc - v1 * ss, o2 = v1 * cc + v0 * ss; st_wt16(kout + (size_t)row * 256 + hd * 64 + d, o1); st_wt16(kout + (size_t)row * 256 + hd * 64 + 32 + d, o2);
;                 u32x2v w1, w2; w1.x = cvt_pk_bf16(o1[0], o1[1]); w1.y = cvt_pk_bf16(o1[2], o1[3]); w2.x = cvt_pk_bf16(o2[0], o2[1]); w2.y = cvt_pk_bf16(o2[2], o2[3]);
;                 bf16_t* dst = AKB + (size_t)row * 256 + hd * 64 + d; st_wt8(dst, w1); st_wt8(dst + 32, w2); })
.LBB0_310:
	v_lshl_add_u32 v163, v162, 3, s31
	v_lshrrev_b32_e32 v144, 1, v163
	v_readlane_b32 s40, v249, 4
	v_readlane_b32 s2, v250, 23
	v_and_b32_e32 v172, 28, v144
	v_readlane_b32 s42, v249, 6
	v_readlane_b32 s43, v249, 7
	v_readlane_b32 s3, v250, 24
	v_lshlrev_b32_e32 v144, 2, v172
	v_lshl_add_u64 v[146:147], s[42:43], 0, v[214:215]
	v_mov_b32_e32 v145, v215
	v_lshl_add_u64 v[152:153], s[2:3], 0, v[214:215]
	v_lshl_add_u64 v[150:151], v[146:147], 0, v[144:145]
	v_lshl_add_u64 v[152:153], v[152:153], 0, v[144:145]
	global_load_dwordx4 v[146:149], v[150:151], off
	global_load_dwordx4 v[154:157], v[152:153], off
	v_ashrrev_i32_e32 v143, 31, v142
	v_readlane_b32 s22, v250, 39
	v_readlane_b32 s23, v250, 40
	v_lshlrev_b32_e32 v214, 1, v172
	s_mov_b64 s[24:25], 0x200
	s_mov_b64 s[38:39], 0x280
	s_mov_b32 s40, 0xf800000
	v_readlane_b32 s41, v249, 5
	s_waitcnt vmcnt(0)
	v_mov_b32_e32 v178, v146
	v_mov_b32_e32 v179, v147
	v_mov_b32_e32 v180, v148
	v_mov_b32_e32 v181, v149
	v_mov_b32_e32 v182, v154
	v_mov_b32_e32 v183, v155
	v_mov_b32_e32 v184, v156
	v_mov_b32_e32 v185, v157
	v_pk_mul_f32 v[164:165], v[124:125], v[156:157]
	v_pk_mul_f32 v[168:169], v[122:123], v[154:155]
	v_pk_fma_f32 v[166:167], v[128:129], v[148:149], v[164:165] neg_lo:[0,0,1] neg_hi:[0,0,1]
	v_pk_fma_f32 v[164:165], v[126:127], v[146:147], v[168:169] neg_lo:[0,0,1] neg_hi:[0,0,1]
	v_pk_mul_f32 v[154:155], v[126:127], v[154:155]
	v_and_b32_e32 v168, 0xffffffc0, v163
	v_pk_mul_f32 v[156:157], v[128:129], v[156:157]
	v_pk_fma_f32 v[154:155], v[122:123], v[146:147], v[154:155]
	v_lshlrev_b64 v[146:147], 10, v[142:143]
	v_ashrrev_i32_e32 v169, 31, v168
	v_pk_fma_f32 v[156:157], v[124:125], v[148:149], v[156:157]
	v_lshl_add_u64 v[148:149], s[6:7], 0, v[146:147]
	v_lshlrev_b64 v[146:147], 2, v[168:169]
	v_lshl_add_u64 v[148:149], v[148:149], 0, v[146:147]
	v_lshl_add_u64 v[170:171], v[148:149], 0, v[144:145]
	global_store_dwordx4 v[170:171], v[164:167], off sc1
	s_nop 1
	v_lshl_add_u64 v[148:149], v[170:171], 0, s[92:93]
	global_store_dwordx4 v[148:149], v[154:157], off sc1
	s_nop 1
	v_lshlrev_b64 v[148:149], 9, v[142:143]
	v_cvt_pk_bf16_f32 v164, v164, v165
	v_cvt_pk_bf16_f32 v165, v166, v167
	v_cvt_pk_bf16_f32 v154, v154, v155
	v_cvt_pk_bf16_f32 v155, v156, v157
	v_lshl_add_u64 v[156:157], s[22:23], 0, v[148:149]
	v_lshlrev_b64 v[148:149], 1, v[168:169]
	v_lshl_add_u64 v[156:157], v[156:157], 0, v[148:149]
	v_lshl_add_u64 v[168:169], v[156:157], 0, v[214:215]
	global_store_dwordx2 v[168:169], v[164:165], off
	global_store_dwordx2 v[168:169], v[154:155], off offset:64
	v_mov_b32_e32 v154, v178
	v_mov_b32_e32 v155, v179
	v_mov_b32_e32 v156, v180
	v_mov_b32_e32 v157, v181
	s_nop 0
	v_mov_b32_e32 v150, v182
	v_mov_b32_e32 v151, v183
	v_mov_b32_e32 v152, v184
	v_mov_b32_e32 v153, v185
	s_nop 0
	v_pk_mul_f32 v[164:165], v[116:117], v[152:153]
	v_pk_mul_f32 v[172:173], v[114:115], v[150:151]
	v_pk_mul_f32 v[150:151], v[118:119], v[150:151]
	v_pk_fma_f32 v[166:167], v[120:121], v[156:157], v[164:165] neg_lo:[0,0,1] neg_hi:[0,0,1]
	v_pk_fma_f32 v[164:165], v[118:119], v[154:155], v[172:173] neg_lo:[0,0,1] neg_hi:[0,0,1]
	v_pk_fma_f32 v[150:151], v[114:115], v[154:155], v[150:151]
	v_lshl_add_u64 v[154:155], v[170:171], 0, s[24:25]
	v_pk_mul_f32 v[152:153], v[120:121], v[152:153]
	global_store_dwordx4 v[154:155], v[164:167], off sc1
	s_nop 1
	v_lshl_add_u64 v[154:155], v[170:171], 0, s[38:39]
	v_pk_fma_f32 v[152:153], v[116:117], v[156:157], v[152:153]
	s_nop 0
	global_store_dwordx4 v[154:155], v[150:153], off sc1
	s_nop 1
	v_cvt_pk_bf16_f32 v154, v164, v165
	v_cvt_pk_bf16_f32 v155, v166, v167
	v_cvt_pk_bf16_f32 v150, v150, v151
	v_cvt_pk_bf16_f32 v151, v152, v153
	global_store_dwordx2 v[168:169], v[154:155], off offset:256
	global_store_dwordx2 v[168:169], v[150:151], off offset:320
	v_add_u32_e32 v154, 16, v142
	v_lshlrev_b32_e32 v143, 7, v154
	v_and_b32_e32 v152, 0x7ff80, v143
	v_mov_b32_e32 v153, v215
	v_lshl_add_u64 v[150:151], s[42:43], 0, v[152:153]
	v_lshl_add_u64 v[152:153], s[2:3], 0, v[152:153]
	v_lshl_add_u64 v[150:151], v[150:151], 0, v[144:145]
	v_lshl_add_u64 v[152:153], v[152:153], 0, v[144:145]
	global_load_dwordx4 v[164:167], v[150:151], off
	global_load_dwordx4 v[168:171], v[152:153], off
	v_ashrrev_i32_e32 v155, 31, v154
	s_waitcnt vmcnt(0)
; __device__ __forceinline__ unsigned cvt_pk_bf16(float lo, float hi) { unsigned r; asm volatile("v_cvt_pk_bf16_f32 %0, %1, %2" : "=v"(r) : "v"(lo), "v"(hi)); return r; }
; template <class V> __device__ __forceinline__ void st_wt16(void* p, const V v) { static_assert(sizeof(V) == 16, "16-byte value"); asm volatile("global_store_dwordx4 %0, %1, off sc1\n\ts_nop 1" ::"v"(p), "v"(v) : "memory"); }
; template <class V> __device__ __forceinline__ void st_wt8(void* p, const V v) { static_assert(sizeof(V) == 8, "8-byte value"); *(V*)p = v; }
; #define EPIIN_LOOP(...) _Pragma("unroll") for (int ai = 0; ai < 2; ++ai) _Pragma("unroll") for (int m = 0; m < 4; ++m) { const int row = row0 + ai * HALF + m * 16, t = row & (seq - 1); (void)t; \
;         _Pragma("unroll") for (int bj = 0; bj < 2; ++bj) { const int within = bj * HALF + wc * 32 + 8 * fq; const f32x4 v0 = acc[ai][bj][m][0], v1 = acc[ai][bj][m][1]; __VA_ARGS__ } }
;     __device__ __forceinline__ void operator()(const f32x4 (&acc)[2][2][4][2], const Unit& u, int wr, int wc, int fr, int fq) const {
;     ...
;         } else if (pn == 9) {
;             EPIIN_LOOP({ const int hd = within >> 6, d = ((within & 63) >> 3) * 4; const f32x4 cc = *(const f32x4*)(rc + (size_t)t * 32 + d), ss = *(const f32x4*)(rs + (size_t)t * 32 + d);
;                 const f32x4 o1 = v0 * cc - v1 * ss, o2 = v1 * cc + v0 * ss; st_wt16(kout + (size_t)row * 256 + hd * 64 + d, o1); st_wt16(kout + (size_t)row * 256 + hd * 64 + 32 + d, o2);
;                 u32x2v w1, w2; w1.x = cvt_pk_bf16(o1[0], o1[1]); w1.y = cvt_pk_bf16(o1[2], o1[3]); w2.x = cvt_pk_bf16(o2[0], o2[1]); w2.y = cvt_pk_bf16(o2[2], o2[3]);
;                 bf16_t* dst = AKB + (size_t)row * 256 + hd * 64 + d; st_wt8(dst, w1); st_wt8(dst + 32, w2); })
	v_mov_b32_e32 v178, v164
	v_mov_b32_e32 v179, v165
	v_mov_b32_e32 v180, v166
	v_mov_b32_e32 v181, v167
	v_mov_b32_e32 v182, v168
	v_mov_b32_e32 v183, v169
	v_mov_b32_e32 v184, v170
	v_mov_b32_e32 v185, v171
	v_pk_mul_f32 v[156:157], v[108:109], v[170:171]
	s_nop 0
	v_pk_fma_f32 v[174:175], v[112:113], v[166:167], v[156:157] neg_lo:[0,0,1] neg_hi:[0,0,1]
	v_pk_mul_f32 v[156:157], v[112:113], v[170:171]
	v_pk_mul_f32 v[172:173], v[106:107], v[168:169]
	v_pk_fma_f32 v[166:167], v[108:109], v[166:167], v[156:157]
	v_lshlrev_b64 v[156:157], 10, v[154:155]
	v_lshl_add_u64 v[156:157], s[6:7], 0, v[156:157]
	v_pk_mul_f32 v[168:169], v[110:111], v[168:169]
	v_lshl_add_u64 v[156:157], v[156:157], 0, v[146:147]
	v_lshlrev_b64 v[154:155], 9, v[154:155]
	v_pk_fma_f32 v[172:173], v[110:111], v[164:165], v[172:173] neg_lo:[0,0,1] neg_hi:[0,0,1]
	v_pk_fma_f32 v[164:165], v[106:107], v[164:165], v[168:169]
	v_lshl_add_u64 v[168:169], v[156:157], 0, v[144:145]
	v_lshl_add_u64 v[154:155], s[22:23], 0, v[154:155]
	global_store_dwordx4 v[168:169], v[172:175], off sc1
	s_nop 1
	v_lshl_add_u64 v[156:157], v[168:169], 0, s[92:93]
	v_lshl_add_u64 v[154:155], v[154:155], 0, v[148:149]
	global_store_dwordx4 v[156:157], v[164:167], off sc1
	s_nop 1
	v_cvt_pk_bf16_f32 v156, v172, v173
	v_cvt_pk_bf16_f32 v157, v174, v175
	v_lshl_add_u64 v[170:171], v[154:155], 0, v[214:215]
	v_cvt_pk_bf16_f32 v164, v164, v165
	v_cvt_pk_bf16_f32 v165, v166, v167
	global_store_dwordx2 v[170:171], v[156:157], off
	global_store_dwordx2 v[170:171], v[164:165], off offset:64
	v_mov_b32_e32 v154, v178
	v_mov_b32_e32 v155, v179
	v_mov_b32_e32 v156, v180
	v_mov_b32_e32 v157, v181
	s_nop 0
	v_mov_b32_e32 v150, v182
	v_mov_b32_e32 v151, v183
	v_mov_b32_e32 v152, v184
	v_mov_b32_e32 v153, v185
	s_nop 0
	v_pk_mul_f32 v[164:165], v[100:101], v[152:153]
	v_pk_mul_f32 v[172:173], v[98:99], v[150:151]
	v_pk_mul_f32 v[150:151], v[102:103], v[150:151]
	v_pk_fma_f32 v[166:167], v[104:105], v[156:157], v[164:165] neg_lo:[0,0,1] neg_hi:[0,0,1]
	v_pk_fma_f32 v[164:165], v[102:103], v[154:155], v[172:173] neg_lo:[0,0,1] neg_hi:[0,0,1]
	v_pk_fma_f32 v[150:151], v[98:99], v[154:155], v[150:151]
	v_lshl_add_u64 v[154:155], v[168:169], 0, s[24:25]
	v_pk_mul_f32 v[152:153], v[104:105], v[152:153]
	global_store_dwordx4 v[154:155], v[164:167], off sc1
	s_nop 1
	v_lshl_add_u64 v[154:155], v[168:169], 0, s[38:39]
	v_pk_fma_f32 v[152:153], v[100:101], v[156:157], v[152:153]
	s_nop 0
	global_store_dwordx4 v[154:155], v[150:153], off sc1
	s_nop 1
	v_cvt_pk_bf16_f32 v154, v164, v165
	v_cvt_pk_bf16_f32 v155, v166, v167
	v_cvt_pk_bf16_f32 v150, v150, v151
	v_cvt_pk_bf16_f32 v151, v152, v153
	global_store_dwordx2 v[170:171], v[154:155], off offset:256
	global_store_dwordx2 v[170:171], v[150:151], off offset:320
	v_add_u32_e32 v154, 32, v142
	v_lshlrev_b32_e32 v143, 7, v154
	v_and_b32_e32 v152, 0x7ff80, v143
	v_mov_b32_e32 v153, v215
	v_lshl_add_u64 v[150:151], s[42:43], 0, v[152:153]
	v_lshl_add_u64 v[152:153], s[2:3], 0, v[152:153]
	v_lshl_add_u64 v[150:151], v[150:151], 0, v[144:145]
	v_lshl_add_u64 v[152:153], v[152:153], 0, v[144:145]
	global_load_dwordx4 v[164:167], v[150:151], off
	global_load_dwordx4 v[168:171], v[152:153], off
	v_ashrrev_i32_e32 v155, 31, v154
	s_waitcnt vmcnt(0)
	v_mov_b32_e32 v178, v164
	v_mov_b32_e32 v179, v165
	v_mov_b32_e32 v180, v166
	v_mov_b32_e32 v181, v167
	v_mov_b32_e32 v182, v168
	v_mov_b32_e32 v183, v169
	v_mov_b32_e32 v184, v170
	v_mov_b32_e32 v185, v171
	v_pk_mul_f32 v[156:157], v[92:93], v[170:171]
	s_nop 0
	v_pk_fma_f32 v[174:175], v[96:97], v[166:167], v[156:157] neg_lo:[0,0,1] neg_hi:[0,0,1]
	v_pk_mul_f32 v[156:157], v[96:97], v[170:171]
	v_pk_mul_f32 v[172:173], v[90:91], v[168:169]
	v_pk_fma_f32 v[166:167], v[92:93], v[166:167], v[156:157]
	v_lshlrev_b64 v[156:157], 10, v[154:155]
	v_lshl_add_u64 v[156:157], s[6:7], 0, v[156:157]
	v_pk_mul_f32 v[168:169], v[94:95], v[168:169]
	v_lshl_add_u64 v[156:157], v[156:157], 0, v[146:147]
	v_lshlrev_b64 v[154:155], 9, v[154:155]
	v_pk_fma_f32 v[172:173], v[94:95], v[164:165], v[172:173] neg_lo:[0,0,1] neg_hi:[0,0,1]
	v_pk_fma_f32 v[164:165], v[90:91], v[164:165], v[168:169]
	v_lshl_add_u64 v[168:169], v[156:157], 0, v[144:145]
	v_lshl_add_u64 v[154:155], s[22:23], 0, v[154:155]
	global_store_dwordx4 v[168:169], v[172:175], off sc1
	s_nop 1
	v_lshl_add_u64 v[156:157], v[168:169], 0, s[92:93]
	v_lshl_add_u64 v[154:155], v[154:155], 0, v[148:149]
	global_store_dwordx4 v[156:157], v[164:167], off sc1
	s_nop 1
	v_cvt_pk_bf16_f32 v156, v172, v173
	v_cvt_pk_bf16_f32 v157, v174, v175
	v_lshl_add_u64 v[170:171], v[154:155], 0, v[214:215]
	v_cvt_pk_bf16_f32 v164, v164, v165
	v_cvt_pk_bf16_f32 v165, v166, v167
	global_store_dwordx2 v[170:171], v[156:157], off
	global_store_dwordx2 v[170:171], v[164:165], off offset:64
	v_mov_b32_e32 v154, v178
	v_mov_b32_e32 v155, v179
	v_mov_b32_e32 v156, v180
	v_mov_b32_e32 v157, v181
	s_nop 0
	v_mov_b32_e32 v150, v182
	v_mov_b32_e32 v151, v183
	v_mov_b32_e32 v152, v184
	v_mov_b32_e32 v153, v185
	s_nop 0
	v_pk_mul_f32 v[164:165], v[84:85], v[152:153]
	v_pk_mul_f32 v[172:173], v[82:83], v[150:151]
	v_pk_mul_f32 v[150:151], v[86:87], v[150:151]
	v_pk_fma_f32 v[166:167], v[88:89], v[156:157], v[164:165] neg_lo:[0,0,1] neg_hi:[0,0,1]
	v_pk_fma_f32 v[164:165], v[86:87], v[154:155], v[172:173] neg_lo:[0,0,1] neg_hi:[0,0,1]
	v_pk_fma_f32 v[150:151], v[82:83], v[154:155], v[150:151]
	v_lshl_add_u64 v[154:155], v[168:169], 0, s[24:25]
	v_pk_mul_f32 v[152:153], v[88:89], v[152:153]
	global_store_dwordx4 v[154:155], v[164:167], off sc1
	s_nop 1
	v_lshl_add_u64 v[154:155], v[168:169], 0, s[38:39]
	v_pk_fma_f32 v[152:153], v[84:85], v[156:157], v[152:153]
	s_nop 0
	global_store_dwordx4 v[154:155], v[150:153], off sc1
	s_nop 1
	v_cvt_pk_bf16_f32 v154, v164, v165
	v_cvt_pk_bf16_f32 v155, v166, v167
	v_cvt_pk_bf16_f32 v150, v150, v151
	v_cvt_pk_bf16_f32 v151, v152, v153
	global_store_dwordx2 v[170:171], v[154:155], off offset:256
	global_store_dwordx2 v[170:171], v[150:151], off offset:320
	v_add_u32_e32 v154, 48, v142
	v_lshlrev_b32_e32 v143, 7, v154
	v_and_b32_e32 v152, 0x7ff80, v143
	v_mov_b32_e32 v153, v215
	v_lshl_add_u64 v[150:151], s[42:43], 0, v[152:153]
	v_lshl_add_u64 v[152:153], s[2:3], 0, v[152:153]
	v_lshl_add_u64 v[150:151], v[150:151], 0, v[144:145]
	v_lshl_add_u64 v[152:153], v[152:153], 0, v[144:145]
	global_load_dwordx4 v[164:167], v[150:151], off
	global_load_dwordx4 v[168:171], v[152:153], off
	v_ashrrev_i32_e32 v155, 31, v154
	s_waitcnt vmcnt(0)
; __device__ __forceinline__ unsigned cvt_pk_bf16(float lo, float hi) { unsigned r; asm volatile("v_cvt_pk_bf16_f32 %0, %1, %2" : "=v"(r) : "v"(lo), "v"(hi)); return r; }
; template <class V> __device__ __forceinline__ void st_wt16(void* p, const V v) { static_assert(sizeof(V) == 16, "16-byte value"); asm volatile("global_store_dwordx4 %0, %1, off sc1\n\ts_nop 1" ::"v"(p), "v"(v) : "memory"); }
; template <class V> __device__ __forceinline__ void st_wt8(void* p, const V v) { static_assert(sizeof(V) == 8, "8-byte value"); *(V*)p = v; }
; #define EPIIN_LOOP(...) _Pragma("unroll") for (int ai = 0; ai < 2; ++ai) _Pragma("unroll") for (int m = 0; m < 4; ++m) { const int row = row0 + ai * HALF + m * 16, t = row & (seq - 1); (void)t; \
;         _Pragma("unroll") for (int bj = 0; bj < 2; ++bj) { const int within = bj * HALF + wc * 32 + 8 * fq; const f32x4 v0 = acc[ai][bj][m][0], v1 = acc[ai][bj][m][1]; __VA_ARGS__ } }
;     __device__ __forceinline__ void operator()(const f32x4 (&acc)[2][2][4][2], const Unit& u, int wr, int wc, int fr, int fq) const {
;     ...
;         } else if (pn == 9) {
;             EPIIN_LOOP({ const int hd = within >> 6, d = ((within & 63) >> 3) * 4; const f32x4 cc = *(const f32x4*)(rc + (size_t)t * 32 + d), ss = *(const f32x4*)(rs + (size_t)t * 32 + d);
;                 const f32x4 o1 = v0 * cc - v1 * ss, o2 = v1 * cc + v0 * ss; st_wt16(kout + (size_t)row * 256 + hd * 64 + d, o1); st_wt16(kout + (size_t)row * 256 + hd * 64 + 32 + d, o2);
;                 u32x2v w1, w2; w1.x = cvt_pk_bf16(o1[0], o1[1]); w1.y = cvt_pk_bf16(o1[2], o1[3]); w2.x = cvt_pk_bf16(o2[0], o2[1]); w2.y = cvt_pk_bf16(o2[2], o2[3]);
;                 bf16_t* dst = AKB + (size_t)row * 256 + hd * 64 + d; st_wt8(dst, w1); st_wt8(dst + 32, w2); })
	v_mov_b32_e32 v178, v164
	v_mov_b32_e32 v179, v165
	v_mov_b32_e32 v180, v166
	v_mov_b32_e32 v181, v167
	v_mov_b32_e32 v182, v168
	v_mov_b32_e32 v183, v169
	v_mov_b32_e32 v184, v170
	v_mov_b32_e32 v185, v171
	v_pk_mul_f32 v[156:157], v[76:77], v[170:171]
	s_nop 0
	v_pk_fma_f32 v[174:175], v[80:81], v[166:167], v[156:157] neg_lo:[0,0,1] neg_hi:[0,0,1]
	v_pk_mul_f32 v[156:157], v[80:81], v[170:171]
	v_pk_mul_f32 v[172:173], v[74:75], v[168:169]
	v_pk_fma_f32 v[166:167], v[76:77], v[166:167], v[156:157]
	v_lshlrev_b64 v[156:157], 10, v[154:155]
	v_lshl_add_u64 v[156:157], s[6:7], 0, v[156:157]
	v_pk_mul_f32 v[168:169], v[78:79], v[168:169]
	v_lshl_add_u64 v[156:157], v[156:157], 0, v[146:147]
	v_lshlrev_b64 v[154:155], 9, v[154:155]
	v_pk_fma_f32 v[172:173], v[78:79], v[164:165], v[172:173] neg_lo:[0,0,1] neg_hi:[0,0,1]
	v_pk_fma_f32 v[164:165], v[74:75], v[164:165], v[168:169]
	v_lshl_add_u64 v[168:169], v[156:157], 0, v[144:145]
	v_lshl_add_u64 v[154:155], s[22:23], 0, v[154:155]
	global_store_dwordx4 v[168:169], v[172:175], off sc1
	s_nop 1
	v_lshl_add_u64 v[156:157], v[168:169], 0, s[92:93]
	v_lshl_add_u64 v[154:155], v[154:155], 0, v[148:149]
	global_store_dwordx4 v[156:157], v[164:167], off sc1
	s_nop 1
	v_cvt_pk_bf16_f32 v156, v172, v173
	v_cvt_pk_bf16_f32 v157, v174, v175
	v_lshl_add_u64 v[170:171], v[154:155], 0, v[214:215]
	v_cvt_pk_bf16_f32 v164, v164, v165
	v_cvt_pk_bf16_f32 v165, v166, v167
	global_store_dwordx2 v[170:171], v[156:157], off
	global_store_dwordx2 v[170:171], v[164:165], off offset:64
	v_mov_b32_e32 v154, v178
	v_mov_b32_e32 v155, v179
	v_mov_b32_e32 v156, v180
	v_mov_b32_e32 v157, v181
	s_nop 0
	v_mov_b32_e32 v150, v182
	v_mov_b32_e32 v151, v183
	v_mov_b32_e32 v152, v184
	v_mov_b32_e32 v153, v185
	s_nop 0
	v_pk_mul_f32 v[164:165], v[68:69], v[152:153]
	v_pk_mul_f32 v[172:173], v[66:67], v[150:151]
	v_pk_mul_f32 v[150:151], v[70:71], v[150:151]
	v_pk_fma_f32 v[166:167], v[72:73], v[156:157], v[164:165] neg_lo:[0,0,1] neg_hi:[0,0,1]
	v_pk_fma_f32 v[164:165], v[70:71], v[154:155], v[172:173] neg_lo:[0,0,1] neg_hi:[0,0,1]
	v_pk_fma_f32 v[150:151], v[66:67], v[154:155], v[150:151]
	v_lshl_add_u64 v[154:155], v[168:169], 0, s[24:25]
	v_pk_mul_f32 v[152:153], v[72:73], v[152:153]
	global_store_dwordx4 v[154:155], v[164:167], off sc1
	s_nop 1
	v_lshl_add_u64 v[154:155], v[168:169], 0, s[38:39]
	v_pk_fma_f32 v[152:153], v[68:69], v[156:157], v[152:153]
	s_nop 0
	global_store_dwordx4 v[154:155], v[150:153], off sc1
	s_nop 1
	v_cvt_pk_bf16_f32 v154, v164, v165
	v_cvt_pk_bf16_f32 v155, v166, v167
	v_cvt_pk_bf16_f32 v150, v150, v151
	v_cvt_pk_bf16_f32 v151, v152, v153
	global_store_dwordx2 v[170:171], v[154:155], off offset:256
	global_store_dwordx2 v[170:171], v[150:151], off offset:320
	v_add_u32_e32 v154, 0x80, v142
	v_lshlrev_b32_e32 v143, 7, v154
	v_and_b32_e32 v152, 0x7ff80, v143
	v_mov_b32_e32 v153, v215
	v_lshl_add_u64 v[150:151], s[42:43], 0, v[152:153]
	v_lshl_add_u64 v[152:153], s[2:3], 0, v[152:153]
	v_lshl_add_u64 v[150:151], v[150:151], 0, v[144:145]
	v_lshl_add_u64 v[152:153], v[152:153], 0, v[144:145]
	global_load_dwordx4 v[164:167], v[150:151], off
	global_load_dwordx4 v[168:171], v[152:153], off
	v_ashrrev_i32_e32 v155, 31, v154
	s_waitcnt vmcnt(0)
	v_mov_b32_e32 v178, v164
	v_mov_b32_e32 v179, v165
	v_mov_b32_e32 v180, v166
	v_mov_b32_e32 v181, v167
	v_mov_b32_e32 v182, v168
	v_mov_b32_e32 v183, v169
	v_mov_b32_e32 v184, v170
	v_mov_b32_e32 v185, v171
	v_pk_mul_f32 v[156:157], v[60:61], v[170:171]
	s_nop 0
	v_pk_fma_f32 v[174:175], v[64:65], v[166:167], v[156:157] neg_lo:[0,0,1] neg_hi:[0,0,1]
	v_pk_mul_f32 v[156:157], v[64:65], v[170:171]
	v_pk_mul_f32 v[172:173], v[58:59], v[168:169]
	v_pk_fma_f32 v[166:167], v[60:61], v[166:167], v[156:157]
	v_lshlrev_b64 v[156:157], 10, v[154:155]
	v_lshl_add_u64 v[156:157], s[6:7], 0, v[156:157]
	v_pk_mul_f32 v[168:169], v[62:63], v[168:169]
	v_lshl_add_u64 v[156:157], v[156:157], 0, v[146:147]
	v_lshlrev_b64 v[154:155], 9, v[154:155]
	v_pk_fma_f32 v[172:173], v[62:63], v[164:165], v[172:173] neg_lo:[0,0,1] neg_hi:[0,0,1]
	v_pk_fma_f32 v[164:165], v[58:59], v[164:165], v[168:169]
	v_lshl_add_u64 v[168:169], v[156:157], 0, v[144:145]
	v_lshl_add_u64 v[154:155], s[22:23], 0, v[154:155]
	global_store_dwordx4 v[168:169], v[172:175], off sc1
	s_nop 1
	v_lshl_add_u64 v[156:157], v[168:169], 0, s[92:93]
	v_lshl_add_u64 v[154:155], v[154:155], 0, v[148:149]
	global_store_dwordx4 v[156:157], v[164:167], off sc1
	s_nop 1
	v_cvt_pk_bf16_f32 v156, v172, v173
	v_cvt_pk_bf16_f32 v157, v174, v175
	v_lshl_add_u64 v[170:171], v[154:155], 0, v[214:215]
	v_cvt_pk_bf16_f32 v164, v164, v165
	v_cvt_pk_bf16_f32 v165, v166, v167
	global_store_dwordx2 v[170:171], v[156:157], off
	global_store_dwordx2 v[170:171], v[164:165], off offset:64
	v_mov_b32_e32 v154, v178
	v_mov_b32_e32 v155, v179
	v_mov_b32_e32 v156, v180
	v_mov_b32_e32 v157, v181
	s_nop 0
	v_mov_b32_e32 v150, v182
	v_mov_b32_e32 v151, v183
	v_mov_b32_e32 v152, v184
	v_mov_b32_e32 v153, v185
	s_nop 0
	v_pk_mul_f32 v[164:165], v[52:53], v[152:153]
	v_pk_mul_f32 v[172:173], v[50:51], v[150:151]
	v_pk_mul_f32 v[150:151], v[54:55], v[150:151]
	v_pk_fma_f32 v[166:167], v[56:57], v[156:157], v[164:165] neg_lo:[0,0,1] neg_hi:[0,0,1]
	v_pk_fma_f32 v[164:165], v[54:55], v[154:155], v[172:173] neg_lo:[0,0,1] neg_hi:[0,0,1]
	v_pk_fma_f32 v[150:151], v[50:51], v[154:155], v[150:151]
	v_lshl_add_u64 v[154:155], v[168:169], 0, s[24:25]
	v_pk_mul_f32 v[152:153], v[56:57], v[152:153]
	global_store_dwordx4 v[154:155], v[164:167], off sc1
	s_nop 1
	v_lshl_add_u64 v[154:155], v[168:169], 0, s[38:39]
	v_pk_fma_f32 v[152:153], v[52:53], v[156:157], v[152:153]
	s_nop 0
	global_store_dwordx4 v[154:155], v[150:153], off sc1
	s_nop 1
	v_cvt_pk_bf16_f32 v154, v164, v165
	v_cvt_pk_bf16_f32 v155, v166, v167
	v_cvt_pk_bf16_f32 v150, v150, v151
	v_cvt_pk_bf16_f32 v151, v152, v153
	global_store_dwordx2 v[170:171], v[154:155], off offset:256
	global_store_dwordx2 v[170:171], v[150:151], off offset:320
	v_add_u32_e32 v154, 0x90, v142
	v_lshlrev_b32_e32 v143, 7, v154
	v_and_b32_e32 v152, 0x7ff80, v143
	v_mov_b32_e32 v153, v215
	v_lshl_add_u64 v[150:151], s[42:43], 0, v[152:153]
	v_lshl_add_u64 v[152:153], s[2:3], 0, v[152:153]
	v_lshl_add_u64 v[150:151], v[150:151], 0, v[144:145]
	v_lshl_add_u64 v[152:153], v[152:153], 0, v[144:145]
	global_load_dwordx4 v[164:167], v[150:151], off
	global_load_dwordx4 v[168:171], v[152:153], off
	v_ashrrev_i32_e32 v155, 31, v154
	s_waitcnt vmcnt(0)
; __device__ __forceinline__ unsigned cvt_pk_bf16(float lo, float hi) { unsigned r; asm volatile("v_cvt_pk_bf16_f32 %0, %1, %2" : "=v"(r) : "v"(lo), "v"(hi)); return r; }
; template <class V> __device__ __forceinline__ void st_wt16(void* p, const V v) { static_assert(sizeof(V) == 16, "16-byte value"); asm volatile("global_store_dwordx4 %0, %1, off sc1\n\ts_nop 1" ::"v"(p), "v"(v) : "memory"); }
; template <class V> __device__ __forceinline__ void st_wt8(void* p, const V v) { static_assert(sizeof(V) == 8, "8-byte value"); *(V*)p = v; }
; #define EPIIN_LOOP(...) _Pragma("unroll") for (int ai = 0; ai < 2; ++ai) _Pragma("unroll") for (int m = 0; m < 4; ++m) { const int row = row0 + ai * HALF + m * 16, t = row & (seq - 1); (void)t; \
;         _Pragma("unroll") for (int bj = 0; bj < 2; ++bj) { const int within = bj * HALF + wc * 32 + 8 * fq; const f32x4 v0 = acc[ai][bj][m][0], v1 = acc[ai][bj][m][1]; __VA_ARGS__ } }
;     __device__ __forceinline__ void operator()(const f32x4 (&acc)[2][2][4][2], const Unit& u, int wr, int wc, int fr, int fq) const {
;     ...
;         } else if (pn == 9) {
;             EPIIN_LOOP({ const int hd = within >> 6, d = ((within & 63) >> 3) * 4; const f32x4 cc = *(const f32x4*)(rc + (size_t)t * 32 + d), ss = *(const f32x4*)(rs + (size_t)t * 32 + d);
;                 const f32x4 o1 = v0 * cc - v1 * ss, o2 = v1 * cc + v0 * ss; st_wt16(kout + (size_t)row * 256 + hd * 64 + d, o1); st_wt16(kout + (size_t)row * 256 + hd * 64 + 32 + d, o2);
;                 u32x2v w1, w2; w1.x = cvt_pk_bf16(o1[0], o1[1]); w1.y = cvt_pk_bf16(o1[2], o1[3]); w2.x = cvt_pk_bf16(o2[0], o2[1]); w2.y = cvt_pk_bf16(o2[2], o2[3]);
;                 bf16_t* dst = AKB + (size_t)row * 256 + hd * 64 + d; st_wt8(dst, w1); st_wt8(dst + 32, w2); })
	v_mov_b32_e32 v178, v164
	v_mov_b32_e32 v179, v165
	v_mov_b32_e32 v180, v166
	v_mov_b32_e32 v181, v167
	v_mov_b32_e32 v182, v168
	v_mov_b32_e32 v183, v169
	v_mov_b32_e32 v184, v170
	v_mov_b32_e32 v185, v171
	v_pk_mul_f32 v[156:157], v[44:45], v[170:171]
	s_nop 0
	v_pk_fma_f32 v[174:175], v[48:49], v[166:167], v[156:157] neg_lo:[0,0,1] neg_hi:[0,0,1]
	v_pk_mul_f32 v[156:157], v[48:49], v[170:171]
	v_pk_mul_f32 v[172:173], v[42:43], v[168:169]
	v_pk_fma_f32 v[166:167], v[44:45], v[166:167], v[156:157]
	v_lshlrev_b64 v[156:157], 10, v[154:155]
	v_lshl_add_u64 v[156:157], s[6:7], 0, v[156:157]
	v_pk_mul_f32 v[168:169], v[46:47], v[168:169]
	v_lshl_add_u64 v[156:157], v[156:157], 0, v[146:147]
	v_lshlrev_b64 v[154:155], 9, v[154:155]
	v_pk_fma_f32 v[172:173], v[46:47], v[164:165], v[172:173] neg_lo:[0,0,1] neg_hi:[0,0,1]
	v_pk_fma_f32 v[164:165], v[42:43], v[164:165], v[168:169]
	v_lshl_add_u64 v[168:169], v[156:157], 0, v[144:145]
	v_lshl_add_u64 v[154:155], s[22:23], 0, v[154:155]
	global_store_dwordx4 v[168:169], v[172:175], off sc1
	s_nop 1
	v_lshl_add_u64 v[156:157], v[168:169], 0, s[92:93]
	v_lshl_add_u64 v[154:155], v[154:155], 0, v[148:149]
	global_store_dwordx4 v[156:157], v[164:167], off sc1
	s_nop 1
	v_cvt_pk_bf16_f32 v156, v172, v173
	v_cvt_pk_bf16_f32 v157, v174, v175
	v_lshl_add_u64 v[170:171], v[154:155], 0, v[214:215]
	v_cvt_pk_bf16_f32 v164, v164, v165
	v_cvt_pk_bf16_f32 v165, v166, v167
	global_store_dwordx2 v[170:171], v[156:157], off
	global_store_dwordx2 v[170:171], v[164:165], off offset:64
	v_mov_b32_e32 v154, v178
	v_mov_b32_e32 v155, v179
	v_mov_b32_e32 v156, v180
	v_mov_b32_e32 v157, v181
	s_nop 0
	v_mov_b32_e32 v150, v182
	v_mov_b32_e32 v151, v183
	v_mov_b32_e32 v152, v184
	v_mov_b32_e32 v153, v185
	s_nop 0
	v_pk_mul_f32 v[164:165], v[36:37], v[152:153]
	v_pk_mul_f32 v[172:173], v[34:35], v[150:151]
	v_pk_mul_f32 v[150:151], v[38:39], v[150:151]
	v_pk_fma_f32 v[166:167], v[40:41], v[156:157], v[164:165] neg_lo:[0,0,1] neg_hi:[0,0,1]
	v_pk_fma_f32 v[164:165], v[38:39], v[154:155], v[172:173] neg_lo:[0,0,1] neg_hi:[0,0,1]
	v_pk_fma_f32 v[150:151], v[34:35], v[154:155], v[150:151]
	v_lshl_add_u64 v[154:155], v[168:169], 0, s[24:25]
	v_pk_mul_f32 v[152:153], v[40:41], v[152:153]
	global_store_dwordx4 v[154:155], v[164:167], off sc1
	s_nop 1
	v_lshl_add_u64 v[154:155], v[168:169], 0, s[38:39]
	v_pk_fma_f32 v[152:153], v[36:37], v[156:157], v[152:153]
	s_nop 0
	global_store_dwordx4 v[154:155], v[150:153], off sc1
	s_nop 1
	v_cvt_pk_bf16_f32 v154, v164, v165
	v_cvt_pk_bf16_f32 v155, v166, v167
	v_cvt_pk_bf16_f32 v150, v150, v151
	v_cvt_pk_bf16_f32 v151, v152, v153
	global_store_dwordx2 v[170:171], v[154:155], off offset:256
	global_store_dwordx2 v[170:171], v[150:151], off offset:320
	v_add_u32_e32 v154, 0xa0, v142
	v_lshlrev_b32_e32 v143, 7, v154
	v_and_b32_e32 v152, 0x7ff80, v143
	v_mov_b32_e32 v153, v215
	v_lshl_add_u64 v[150:151], s[42:43], 0, v[152:153]
	v_lshl_add_u64 v[152:153], s[2:3], 0, v[152:153]
	v_lshl_add_u64 v[150:151], v[150:151], 0, v[144:145]
	v_lshl_add_u64 v[152:153], v[152:153], 0, v[144:145]
	global_load_dwordx4 v[164:167], v[150:151], off
	global_load_dwordx4 v[168:171], v[152:153], off
	v_ashrrev_i32_e32 v155, 31, v154
	s_waitcnt vmcnt(0)
; __device__ __forceinline__ unsigned cvt_pk_bf16(float lo, float hi) { unsigned r; asm volatile("v_cvt_pk_bf16_f32 %0, %1, %2" : "=v"(r) : "v"(lo), "v"(hi)); return r; }
; template <class V> __device__ __forceinline__ void st_wt16(void* p, const V v) { static_assert(sizeof(V) == 16, "16-byte value"); asm volatile("global_store_dwordx4 %0, %1, off sc1\n\ts_nop 1" ::"v"(p), "v"(v) : "memory"); }
; template <class V> __device__ __forceinline__ void st_wt8(void* p, const V v) { static_assert(sizeof(V) == 8, "8-byte value"); *(V*)p = v; }
; #define EPIIN_LOOP(...) _Pragma("unroll") for (int ai = 0; ai < 2; ++ai) _Pragma("unroll") for (int m = 0; m < 4; ++m) { const int row = row0 + ai * HALF + m * 16, t = row & (seq - 1); (void)t; \
;         _Pragma("unroll") for (int bj = 0; bj < 2; ++bj) { const int within = bj * HALF + wc * 32 + 8 * fq; const f32x4 v0 = acc[ai][bj][m][0], v1 = acc[ai][bj][m][1]; __VA_ARGS__ } }
;     __device__ __forceinline__ void operator()(const f32x4 (&acc)[2][2][4][2], const Unit& u, int wr, int wc, int fr, int fq) const {
;     ...
;         } else if (pn == 9) {
;             EPIIN_LOOP({ const int hd = within >> 6, d = ((within & 63) >> 3) * 4; const f32x4 cc = *(const f32x4*)(rc + (size_t)t * 32 + d), ss = *(const f32x4*)(rs + (size_t)t * 32 + d);
;                 const f32x4 o1 = v0 * cc - v1 * ss, o2 = v1 * cc + v0 * ss; st_wt16(kout + (size_t)row * 256 + hd * 64 + d, o1); st_wt16(kout + (size_t)row * 256 + hd * 64 + 32 + d, o2);
;                 u32x2v w1, w2; w1.x = cvt_pk_bf16(o1[0], o1[1]); w1.y = cvt_pk_bf16(o1[2], o1[3]); w2.x = cvt_pk_bf16(o2[0], o2[1]); w2.y = cvt_pk_bf16(o2[2], o2[3]);
;                 bf16_t* dst = AKB + (size_t)row * 256 + hd * 64 + d; st_wt8(dst, w1); st_wt8(dst + 32, w2); })
	v_mov_b32_e32 v178, v164
	v_mov_b32_e32 v179, v165
	v_mov_b32_e32 v180, v166
	v_mov_b32_e32 v181, v167
	v_mov_b32_e32 v182, v168
	v_mov_b32_e32 v183, v169
	v_mov_b32_e32 v184, v170
	v_mov_b32_e32 v185, v171
	v_pk_mul_f32 v[156:157], v[28:29], v[170:171]
	s_nop 0
	v_pk_fma_f32 v[174:175], v[32:33], v[166:167], v[156:157] neg_lo:[0,0,1] neg_hi:[0,0,1]
	v_pk_mul_f32 v[156:157], v[32:33], v[170:171]
	v_pk_mul_f32 v[172:173], v[26:27], v[168:169]
	v_pk_fma_f32 v[166:167], v[28:29], v[166:167], v[156:157]
	v_lshlrev_b64 v[156:157], 10, v[154:155]
	v_lshl_add_u64 v[156:157], s[6:7], 0, v[156:157]
	v_pk_mul_f32 v[168:169], v[30:31], v[168:169]
	v_lshl_add_u64 v[156:157], v[156:157], 0, v[146:147]
	v_lshlrev_b64 v[154:155], 9, v[154:155]
	v_pk_fma_f32 v[172:173], v[30:31], v[164:165], v[172:173] neg_lo:[0,0,1] neg_hi:[0,0,1]
	v_pk_fma_f32 v[164:165], v[26:27], v[164:165], v[168:169]
	v_lshl_add_u64 v[168:169], v[156:157], 0, v[144:145]
	v_lshl_add_u64 v[154:155], s[22:23], 0, v[154:155]
	global_store_dwordx4 v[168:169], v[172:175], off sc1
	s_nop 1
	v_lshl_add_u64 v[156:157], v[168:169], 0, s[92:93]
	v_lshl_add_u64 v[154:155], v[154:155], 0, v[148:149]
	global_store_dwordx4 v[156:157], v[164:167], off sc1
	s_nop 1
	v_cvt_pk_bf16_f32 v156, v172, v173
	v_cvt_pk_bf16_f32 v157, v174, v175
	v_lshl_add_u64 v[170:171], v[154:155], 0, v[214:215]
	v_cvt_pk_bf16_f32 v164, v164, v165
	v_cvt_pk_bf16_f32 v165, v166, v167
	global_store_dwordx2 v[170:171], v[156:157], off
	global_store_dwordx2 v[170:171], v[164:165], off offset:64
	v_mov_b32_e32 v154, v178
	v_mov_b32_e32 v155, v179
	v_mov_b32_e32 v156, v180
	v_mov_b32_e32 v157, v181
	s_nop 0
	v_mov_b32_e32 v150, v182
	v_mov_b32_e32 v151, v183
	v_mov_b32_e32 v152, v184
	v_mov_b32_e32 v153, v185
	s_nop 0
	v_pk_mul_f32 v[164:165], v[20:21], v[152:153]
	v_pk_mul_f32 v[172:173], v[18:19], v[150:151]
	v_pk_mul_f32 v[150:151], v[22:23], v[150:151]
	v_pk_fma_f32 v[166:167], v[24:25], v[156:157], v[164:165] neg_lo:[0,0,1] neg_hi:[0,0,1]
	v_pk_fma_f32 v[164:165], v[22:23], v[154:155], v[172:173] neg_lo:[0,0,1] neg_hi:[0,0,1]
	v_pk_fma_f32 v[150:151], v[18:19], v[154:155], v[150:151]
	v_lshl_add_u64 v[154:155], v[168:169], 0, s[24:25]
	v_pk_mul_f32 v[152:153], v[24:25], v[152:153]
	global_store_dwordx4 v[154:155], v[164:167], off sc1
	s_nop 1
	v_lshl_add_u64 v[154:155], v[168:169], 0, s[38:39]
	v_pk_fma_f32 v[152:153], v[20:21], v[156:157], v[152:153]
	s_nop 0
	global_store_dwordx4 v[154:155], v[150:153], off sc1
	s_nop 1
	v_cvt_pk_bf16_f32 v154, v164, v165
	v_cvt_pk_bf16_f32 v155, v166, v167
	v_cvt_pk_bf16_f32 v150, v150, v151
	v_cvt_pk_bf16_f32 v151, v152, v153
	global_store_dwordx2 v[170:171], v[154:155], off offset:256
	global_store_dwordx2 v[170:171], v[150:151], off offset:320
	v_add_u32_e32 v154, 0xb0, v142
	v_lshlrev_b32_e32 v143, 7, v154
	v_and_b32_e32 v152, 0x7ff80, v143
	v_mov_b32_e32 v153, v215
	v_lshl_add_u64 v[150:151], s[42:43], 0, v[152:153]
	v_lshl_add_u64 v[152:153], s[2:3], 0, v[152:153]
	v_lshl_add_u64 v[150:151], v[150:151], 0, v[144:145]
	v_lshl_add_u64 v[152:153], v[152:153], 0, v[144:145]
	global_load_dwordx4 v[164:167], v[150:151], off
	global_load_dwordx4 v[168:171], v[152:153], off
	v_ashrrev_i32_e32 v155, 31, v154
	v_readlane_b32 s42, v254, 41
	v_readlane_b32 s43, v254, 42
	s_waitcnt vmcnt(0)
	v_mov_b32_e32 v178, v164
	v_mov_b32_e32 v179, v165
	v_mov_b32_e32 v180, v166
	v_mov_b32_e32 v181, v167
	v_mov_b32_e32 v182, v168
	v_mov_b32_e32 v183, v169
	v_mov_b32_e32 v184, v170
	v_mov_b32_e32 v185, v171
	v_pk_mul_f32 v[156:157], v[12:13], v[170:171]
	s_nop 0
	v_pk_fma_f32 v[174:175], v[16:17], v[166:167], v[156:157] neg_lo:[0,0,1] neg_hi:[0,0,1]
	v_pk_mul_f32 v[156:157], v[16:17], v[170:171]
	v_pk_mul_f32 v[172:173], v[10:11], v[168:169]
	v_pk_fma_f32 v[166:167], v[12:13], v[166:167], v[156:157]
	v_lshlrev_b64 v[156:157], 10, v[154:155]
	v_lshl_add_u64 v[156:157], s[6:7], 0, v[156:157]
	v_lshl_add_u64 v[146:147], v[156:157], 0, v[146:147]
	v_lshlrev_b64 v[154:155], 9, v[154:155]
	v_pk_mul_f32 v[168:169], v[14:15], v[168:169]
	v_lshl_add_u64 v[156:157], v[146:147], 0, v[144:145]
	v_lshl_add_u64 v[154:155], s[22:23], 0, v[154:155]
	v_pk_fma_f32 v[172:173], v[14:15], v[164:165], v[172:173] neg_lo:[0,0,1] neg_hi:[0,0,1]
	v_pk_fma_f32 v[164:165], v[10:11], v[164:165], v[168:169]
	global_store_dwordx4 v[156:157], v[172:175], off sc1
	s_nop 1
	v_lshl_add_u64 v[144:145], v[156:157], 0, s[92:93]
	v_lshl_add_u64 v[148:149], v[154:155], 0, v[148:149]
	global_store_dwordx4 v[144:145], v[164:167], off sc1
	s_nop 1
	v_cvt_pk_bf16_f32 v144, v172, v173
	v_cvt_pk_bf16_f32 v145, v174, v175
	v_cvt_pk_bf16_f32 v146, v164, v165
	v_lshl_add_u64 v[164:165], v[148:149], 0, v[214:215]
	v_cvt_pk_bf16_f32 v147, v166, v167
	global_store_dwordx2 v[164:165], v[144:145], off
	global_store_dwordx2 v[164:165], v[146:147], off offset:64
	v_mov_b32_e32 v144, v178
	v_mov_b32_e32 v145, v179
	v_mov_b32_e32 v146, v180
	v_mov_b32_e32 v147, v181
	s_nop 0
	v_mov_b32_e32 v148, v182
	v_mov_b32_e32 v149, v183
	v_mov_b32_e32 v150, v184
	v_mov_b32_e32 v151, v185
	s_nop 0
	v_pk_mul_f32 v[152:153], v[4:5], v[150:151]
	v_pk_mul_f32 v[166:167], v[2:3], v[148:149]
	v_pk_mul_f32 v[148:149], v[6:7], v[148:149]
	v_pk_fma_f32 v[154:155], v[8:9], v[146:147], v[152:153] neg_lo:[0,0,1] neg_hi:[0,0,1]
	v_pk_fma_f32 v[152:153], v[6:7], v[144:145], v[166:167] neg_lo:[0,0,1] neg_hi:[0,0,1]
	v_pk_mul_f32 v[150:151], v[8:9], v[150:151]
	v_pk_fma_f32 v[144:145], v[2:3], v[144:145], v[148:149]
	v_lshl_add_u64 v[148:149], v[156:157], 0, s[24:25]
	global_store_dwordx4 v[148:149], v[152:155], off sc1
	s_nop 1
	v_pk_fma_f32 v[146:147], v[4:5], v[146:147], v[150:151]
	v_lshl_add_u64 v[148:149], v[156:157], 0, s[38:39]
	global_store_dwordx4 v[148:149], v[144:147], off sc1
	s_nop 1
	v_cvt_pk_bf16_f32 v148, v152, v153
	v_cvt_pk_bf16_f32 v149, v154, v155
	v_cvt_pk_bf16_f32 v144, v144, v145
	v_cvt_pk_bf16_f32 v145, v146, v147
	global_store_dwordx2 v[164:165], v[148:149], off offset:256
	global_store_dwordx2 v[164:165], v[144:145], off offset:320

; __device__ __forceinline__ unsigned cvt_pk_bf16(float lo, float hi) { unsigned r; asm volatile("v_cvt_pk_bf16_f32 %0, %1, %2" : "=v"(r) : "v"(lo), "v"(hi)); return r; }
; template <class V> __device__ __forceinline__ void st_wt8(void* p, const V v) { static_assert(sizeof(V) == 8, "8-byte value"); *(V*)p = v; }
; #define EPIIN_LOOP(...) _Pragma("unroll") for (int ai = 0; ai < 2; ++ai) _Pragma("unroll") for (int m = 0; m < 4; ++m) { const int row = row0 + ai * HALF + m * 16, t = row & (seq - 1); (void)t; \
;         _Pragma("unroll") for (int bj = 0; bj < 2; ++bj) { const int within = bj * HALF + wc * 32 + 8 * fq; const f32x4 v0 = acc[ai][bj][m][0], v1 = acc[ai][bj][m][1]; __VA_ARGS__ } }
;     __device__ __forceinline__ void operator()(const f32x4 (&acc)[2][2][4][2], const Unit& u, int wr, int wc, int fr, int fq) const {
;     ...
;         } else if (pn == 11) {
;             EPIIN_LOOP({ const int hd = within >> 5, d = ((within & 31) >> 3) * 4; const f32x4 cc = *(const f32x4*)(rc16 + (size_t)t * 16 + d), ss = *(const f32x4*)(rs16 + (size_t)t * 16 + d);
;                 const f32x4 o1 = (v0 * cc - v1 * ss) * qiscale, o2 = (v1 * cc + v0 * ss) * qiscale; u32x2v w1, w2; w1.x = cvt_pk_bf16(o1[0], o1[1]); w1.y = cvt_pk_bf16(o1[2], o1[3]); w2.x = cvt_pk_bf16(o2[0], o2[1]); w2.y = cvt_pk_bf16(o2[2], o2[3]);
;                 st_wt8(QIB + (size_t)row * 256 + hd * 32 + d, w1); st_wt8(QIB + (size_t)row * 256 + hd * 32 + 16 + d, w2); })
.LBB0_350:
	s_cmp_gt_i32 s37, 10
	s_cbranch_scc0 .LBB0_354
	s_cmp_eq_u32 s37, 11
	s_mov_b64 s[22:23], -1
	s_cbranch_scc0 .LBB0_353
	v_lshlrev_b32_e32 v143, 2, v162
	v_lshlrev_b32_e32 v144, 6, v142
	v_readlane_b32 s22, v254, 18
	v_and_b32_e32 v168, 12, v143
	v_and_b32_e32 v214, 0x3ffc0, v144
	v_readlane_b32 s23, v254, 19
	v_readlane_b32 s24, v250, 21
	v_lshlrev_b32_e32 v146, 2, v168
	v_lshl_add_u64 v[144:145], s[22:23], 0, v[214:215]
	v_mov_b32_e32 v147, v215
	v_readlane_b32 s25, v250, 22
	v_lshl_add_u64 v[156:157], v[144:145], 0, v[146:147]
	global_load_dwordx4 v[148:151], v[156:157], off
	v_lshl_add_u64 v[144:145], s[24:25], 0, v[214:215]
	v_lshl_add_u64 v[164:165], v[144:145], 0, v[146:147]
	global_load_dwordx4 v[152:155], v[164:165], off
	s_mov_b32 s44, 0x3e3504f3
	v_ashrrev_i32_e32 v143, 31, v142
	v_readlane_b32 s38, v250, 43
	v_lshl_add_u32 v163, v162, 3, s31
	v_readlane_b32 s39, v250, 44
	v_lshlrev_b32_e32 v214, 1, v168
	s_waitcnt vmcnt(0)
	v_mov_b32_e32 v178, v148
	v_mov_b32_e32 v179, v149
	v_mov_b32_e32 v180, v150
	v_mov_b32_e32 v181, v151
	v_mov_b32_e32 v182, v152
	v_mov_b32_e32 v183, v153
	v_mov_b32_e32 v184, v154
	v_mov_b32_e32 v185, v155
	v_pk_mul_f32 v[144:145], v[124:125], v[154:155]
	v_pk_mul_f32 v[166:167], v[122:123], v[152:153]
	v_pk_fma_f32 v[144:145], v[128:129], v[150:151], v[144:145] neg_lo:[0,0,1] neg_hi:[0,0,1]
	v_pk_mul_f32 v[154:155], v[128:129], v[154:155]
	v_pk_mul_f32 v[152:153], v[126:127], v[152:153]
	v_pk_fma_f32 v[166:167], v[126:127], v[148:149], v[166:167] neg_lo:[0,0,1] neg_hi:[0,0,1]
	v_pk_mul_f32 v[144:145], v[144:145], s[44:45] op_sel_hi:[1,0]
	v_pk_fma_f32 v[150:151], v[124:125], v[150:151], v[154:155]
	v_pk_fma_f32 v[148:149], v[122:123], v[148:149], v[152:153]
	v_pk_mul_f32 v[166:167], v[166:167], s[44:45] op_sel_hi:[1,0]
	v_pk_mul_f32 v[150:151], v[150:151], s[44:45] op_sel_hi:[1,0]
	v_pk_mul_f32 v[148:149], v[148:149], s[44:45] op_sel_hi:[1,0]
	v_cvt_pk_bf16_f32 v152, v166, v167
	v_cvt_pk_bf16_f32 v153, v144, v145
	v_lshlrev_b64 v[144:145], 9, v[142:143]
	v_cvt_pk_bf16_f32 v148, v148, v149
	v_cvt_pk_bf16_f32 v149, v150, v151
	v_lshl_add_u64 v[150:151], s[38:39], 0, v[144:145]
	v_and_b32_e32 v144, 0xffffffe0, v163
	v_ashrrev_i32_e32 v145, 31, v144
	v_lshlrev_b64 v[144:145], 1, v[144:145]
	v_lshl_add_u64 v[150:151], v[150:151], 0, v[144:145]
	v_lshl_add_u64 v[166:167], v[150:151], 0, v[214:215]
	global_store_dwordx2 v[166:167], v[152:153], off
	global_store_dwordx2 v[166:167], v[148:149], off offset:32
	v_mov_b32_e32 v148, v178
	v_mov_b32_e32 v149, v179
	v_mov_b32_e32 v150, v180
	v_mov_b32_e32 v151, v181
	s_nop 0
	v_mov_b32_e32 v152, v182
	v_mov_b32_e32 v153, v183
	v_mov_b32_e32 v154, v184
	v_mov_b32_e32 v155, v185
	s_nop 0
	v_pk_mul_f32 v[156:157], v[116:117], v[154:155]
	v_pk_mul_f32 v[164:165], v[114:115], v[152:153]
	v_pk_fma_f32 v[156:157], v[120:121], v[150:151], v[156:157] neg_lo:[0,0,1] neg_hi:[0,0,1]
	v_pk_fma_f32 v[164:165], v[118:119], v[148:149], v[164:165] neg_lo:[0,0,1] neg_hi:[0,0,1]
	v_pk_mul_f32 v[156:157], v[156:157], s[44:45] op_sel_hi:[1,0]
	v_pk_mul_f32 v[154:155], v[120:121], v[154:155]
	v_pk_mul_f32 v[152:153], v[118:119], v[152:153]
	v_pk_mul_f32 v[164:165], v[164:165], s[44:45] op_sel_hi:[1,0]
	v_pk_fma_f32 v[150:151], v[116:117], v[150:151], v[154:155]
	v_pk_fma_f32 v[148:149], v[114:115], v[148:149], v[152:153]
	v_cvt_pk_bf16_f32 v152, v164, v165
	v_cvt_pk_bf16_f32 v153, v156, v157
	v_add_u32_e32 v156, 16, v142
	v_pk_mul_f32 v[150:151], v[150:151], s[44:45] op_sel_hi:[1,0]
	v_pk_mul_f32 v[148:149], v[148:149], s[44:45] op_sel_hi:[1,0]
	v_lshlrev_b32_e32 v143, 6, v156
	v_cvt_pk_bf16_f32 v148, v148, v149
	v_cvt_pk_bf16_f32 v149, v150, v151
	v_and_b32_e32 v150, 0x3ffc0, v143
	v_mov_b32_e32 v151, v215
	global_store_dwordx2 v[166:167], v[152:153], off offset:256
	global_store_dwordx2 v[166:167], v[148:149], off offset:288
	v_lshl_add_u64 v[148:149], s[22:23], 0, v[150:151]
	v_lshl_add_u64 v[150:151], s[24:25], 0, v[150:151]
	v_lshl_add_u64 v[148:149], v[148:149], 0, v[146:147]
	v_lshl_add_u64 v[150:151], v[150:151], 0, v[146:147]
	global_load_dwordx4 v[152:155], v[148:149], off
	global_load_dwordx4 v[164:167], v[150:151], off
	v_ashrrev_i32_e32 v157, 31, v156
	s_waitcnt vmcnt(0)
	v_mov_b32_e32 v178, v152
	v_mov_b32_e32 v179, v153
	v_mov_b32_e32 v180, v154
	v_mov_b32_e32 v181, v155
	v_mov_b32_e32 v182, v164
	v_mov_b32_e32 v183, v165
	v_mov_b32_e32 v184, v166
	v_mov_b32_e32 v185, v167
	v_pk_mul_f32 v[168:169], v[108:109], v[166:167]
	v_pk_mul_f32 v[170:171], v[106:107], v[164:165]
	v_pk_mul_f32 v[166:167], v[112:113], v[166:167]
	v_pk_mul_f32 v[164:165], v[110:111], v[164:165]
	v_pk_fma_f32 v[168:169], v[112:113], v[154:155], v[168:169] neg_lo:[0,0,1] neg_hi:[0,0,1]
	v_pk_fma_f32 v[170:171], v[110:111], v[152:153], v[170:171] neg_lo:[0,0,1] neg_hi:[0,0,1]
	v_pk_fma_f32 v[154:155], v[108:109], v[154:155], v[166:167]
	v_pk_fma_f32 v[152:153], v[106:107], v[152:153], v[164:165]
	v_pk_mul_f32 v[154:155], v[154:155], s[44:45] op_sel_hi:[1,0]
	v_pk_mul_f32 v[152:153], v[152:153], s[44:45] op_sel_hi:[1,0]
	v_pk_mul_f32 v[168:169], v[168:169], s[44:45] op_sel_hi:[1,0]
	v_pk_mul_f32 v[170:171], v[170:171], s[44:45] op_sel_hi:[1,0]
	s_nop 0
	v_cvt_pk_bf16_f32 v164, v170, v171
	v_cvt_pk_bf16_f32 v165, v168, v169
	v_cvt_pk_bf16_f32 v152, v152, v153
	v_cvt_pk_bf16_f32 v153, v154, v155
	v_lshlrev_b64 v[154:155], 9, v[156:157]
	v_lshl_add_u64 v[154:155], s[38:39], 0, v[154:155]
	v_lshl_add_u64 v[154:155], v[154:155], 0, v[144:145]
	v_lshl_add_u64 v[156:157], v[154:155], 0, v[214:215]
	global_store_dwordx2 v[156:157], v[164:165], off
	global_store_dwordx2 v[156:157], v[152:153], off offset:32
; __device__ __forceinline__ unsigned cvt_pk_bf16(float lo, float hi) { unsigned r; asm volatile("v_cvt_pk_bf16_f32 %0, %1, %2" : "=v"(r) : "v"(lo), "v"(hi)); return r; }
; template <class V> __device__ __forceinline__ void st_wt8(void* p, const V v) { static_assert(sizeof(V) == 8, "8-byte value"); *(V*)p = v; }
; #define EPIIN_LOOP(...) _Pragma("unroll") for (int ai = 0; ai < 2; ++ai) _Pragma("unroll") for (int m = 0; m < 4; ++m) { const int row = row0 + ai * HALF + m * 16, t = row & (seq - 1); (void)t; \
;         _Pragma("unroll") for (int bj = 0; bj < 2; ++bj) { const int within = bj * HALF + wc * 32 + 8 * fq; const f32x4 v0 = acc[ai][bj][m][0], v1 = acc[ai][bj][m][1]; __VA_ARGS__ } }
;     __device__ __forceinline__ void operator()(const f32x4 (&acc)[2][2][4][2], const Unit& u, int wr, int wc, int fr, int fq) const {
;     ...
;         } else if (pn == 11) {
;             EPIIN_LOOP({ const int hd = within >> 5, d = ((within & 31) >> 3) * 4; const f32x4 cc = *(const f32x4*)(rc16 + (size_t)t * 16 + d), ss = *(const f32x4*)(rs16 + (size_t)t * 16 + d);
;                 const f32x4 o1 = (v0 * cc - v1 * ss) * qiscale, o2 = (v1 * cc + v0 * ss) * qiscale; u32x2v w1, w2; w1.x = cvt_pk_bf16(o1[0], o1[1]); w1.y = cvt_pk_bf16(o1[2], o1[3]); w2.x = cvt_pk_bf16(o2[0], o2[1]); w2.y = cvt_pk_bf16(o2[2], o2[3]);
;                 st_wt8(QIB + (size_t)row * 256 + hd * 32 + d, w1); st_wt8(QIB + (size_t)row * 256 + hd * 32 + 16 + d, w2); })
	v_mov_b32_e32 v152, v178
	v_mov_b32_e32 v153, v179
	v_mov_b32_e32 v154, v180
	v_mov_b32_e32 v155, v181
	s_nop 0
	v_mov_b32_e32 v148, v182
	v_mov_b32_e32 v149, v183
	v_mov_b32_e32 v150, v184
	v_mov_b32_e32 v151, v185
	s_nop 0
	v_pk_mul_f32 v[164:165], v[100:101], v[150:151]
	v_pk_mul_f32 v[166:167], v[98:99], v[148:149]
	v_pk_mul_f32 v[148:149], v[102:103], v[148:149]
	v_pk_fma_f32 v[164:165], v[104:105], v[154:155], v[164:165] neg_lo:[0,0,1] neg_hi:[0,0,1]
	v_pk_fma_f32 v[166:167], v[102:103], v[152:153], v[166:167] neg_lo:[0,0,1] neg_hi:[0,0,1]
	v_pk_mul_f32 v[150:151], v[104:105], v[150:151]
	v_pk_fma_f32 v[148:149], v[98:99], v[152:153], v[148:149]
	v_pk_mul_f32 v[164:165], v[164:165], s[44:45] op_sel_hi:[1,0]
	v_pk_mul_f32 v[166:167], v[166:167], s[44:45] op_sel_hi:[1,0]
	v_pk_fma_f32 v[150:151], v[100:101], v[154:155], v[150:151]
	v_pk_mul_f32 v[148:149], v[148:149], s[44:45] op_sel_hi:[1,0]
	v_cvt_pk_bf16_f32 v152, v166, v167
	v_cvt_pk_bf16_f32 v153, v164, v165
	v_pk_mul_f32 v[150:151], v[150:151], s[44:45] op_sel_hi:[1,0]
	v_cvt_pk_bf16_f32 v148, v148, v149
	s_nop 0
	v_cvt_pk_bf16_f32 v149, v150, v151
	global_store_dwordx2 v[156:157], v[152:153], off offset:256
	global_store_dwordx2 v[156:157], v[148:149], off offset:288
	v_add_u32_e32 v156, 32, v142
	v_lshlrev_b32_e32 v143, 6, v156
	v_and_b32_e32 v150, 0x3ffc0, v143
	v_mov_b32_e32 v151, v215
	v_lshl_add_u64 v[148:149], s[22:23], 0, v[150:151]
	v_lshl_add_u64 v[150:151], s[24:25], 0, v[150:151]
	v_lshl_add_u64 v[148:149], v[148:149], 0, v[146:147]
	v_lshl_add_u64 v[150:151], v[150:151], 0, v[146:147]
	global_load_dwordx4 v[152:155], v[148:149], off
	global_load_dwordx4 v[164:167], v[150:151], off
	v_ashrrev_i32_e32 v157, 31, v156
	s_waitcnt vmcnt(0)
	v_mov_b32_e32 v178, v152
	v_mov_b32_e32 v179, v153
	v_mov_b32_e32 v180, v154
	v_mov_b32_e32 v181, v155
	v_mov_b32_e32 v182, v164
	v_mov_b32_e32 v183, v165
	v_mov_b32_e32 v184, v166
	v_mov_b32_e32 v185, v167
	v_pk_mul_f32 v[168:169], v[92:93], v[166:167]
	v_pk_mul_f32 v[170:171], v[90:91], v[164:165]
	v_pk_mul_f32 v[166:167], v[96:97], v[166:167]
	v_pk_mul_f32 v[164:165], v[94:95], v[164:165]
	v_pk_fma_f32 v[168:169], v[96:97], v[154:155], v[168:169] neg_lo:[0,0,1] neg_hi:[0,0,1]
	v_pk_fma_f32 v[170:171], v[94:95], v[152:153], v[170:171] neg_lo:[0,0,1] neg_hi:[0,0,1]
	v_pk_fma_f32 v[154:155], v[92:93], v[154:155], v[166:167]
	v_pk_fma_f32 v[152:153], v[90:91], v[152:153], v[164:165]
	v_pk_mul_f32 v[154:155], v[154:155], s[44:45] op_sel_hi:[1,0]
	v_pk_mul_f32 v[152:153], v[152:153], s[44:45] op_sel_hi:[1,0]
	v_pk_mul_f32 v[168:169], v[168:169], s[44:45] op_sel_hi:[1,0]
	v_pk_mul_f32 v[170:171], v[170:171], s[44:45] op_sel_hi:[1,0]
	s_nop 0
	v_cvt_pk_bf16_f32 v164, v170, v171
	v_cvt_pk_bf16_f32 v165, v168, v169
	v_cvt_pk_bf16_f32 v152, v152, v153
	v_cvt_pk_bf16_f32 v153, v154, v155
	v_lshlrev_b64 v[154:155], 9, v[156:157]
	v_lshl_add_u64 v[154:155], s[38:39], 0, v[154:155]
	v_lshl_add_u64 v[154:155], v[154:155], 0, v[144:145]
	v_lshl_add_u64 v[156:157], v[154:155], 0, v[214:215]
	global_store_dwordx2 v[156:157], v[164:165], off
	global_store_dwordx2 v[156:157], v[152:153], off offset:32
	v_mov_b32_e32 v152, v178
	v_mov_b32_e32 v153, v179
	v_mov_b32_e32 v154, v180
	v_mov_b32_e32 v155, v181
	s_nop 0
	v_mov_b32_e32 v148, v182
	v_mov_b32_e32 v149, v183
	v_mov_b32_e32 v150, v184
	v_mov_b32_e32 v151, v185
	s_nop 0
	v_pk_mul_f32 v[164:165], v[84:85], v[150:151]
	v_pk_mul_f32 v[166:167], v[82:83], v[148:149]
	v_pk_mul_f32 v[148:149], v[86:87], v[148:149]
	v_pk_fma_f32 v[164:165], v[88:89], v[154:155], v[164:165] neg_lo:[0,0,1] neg_hi:[0,0,1]
	v_pk_fma_f32 v[166:167], v[86:87], v[152:153], v[166:167] neg_lo:[0,0,1] neg_hi:[0,0,1]
	v_pk_mul_f32 v[150:151], v[88:89], v[150:151]
	v_pk_fma_f32 v[148:149], v[82:83], v[152:153], v[148:149]
	v_pk_mul_f32 v[164:165], v[164:165], s[44:45] op_sel_hi:[1,0]
	v_pk_mul_f32 v[166:167], v[166:167], s[44:45] op_sel_hi:[1,0]
	v_pk_fma_f32 v[150:151], v[84:85], v[154:155], v[150:151]
	v_pk_mul_f32 v[148:149], v[148:149], s[44:45] op_sel_hi:[1,0]
	v_cvt_pk_bf16_f32 v152, v166, v167
	v_cvt_pk_bf16_f32 v153, v164, v165
	v_pk_mul_f32 v[150:151], v[150:151], s[44:45] op_sel_hi:[1,0]
	v_cvt_pk_bf16_f32 v148, v148, v149
	s_nop 0
	v_cvt_pk_bf16_f32 v149, v150, v151
	global_store_dwordx2 v[156:157], v[152:153], off offset:256
	global_store_dwordx2 v[156:157], v[148:149], off offset:288
	v_add_u32_e32 v156, 48, v142
	v_lshlrev_b32_e32 v143, 6, v156
	v_and_b32_e32 v150, 0x3ffc0, v143
	v_mov_b32_e32 v151, v215
	v_lshl_add_u64 v[148:149], s[22:23], 0, v[150:151]
	v_lshl_add_u64 v[150:151], s[24:25], 0, v[150:151]
	v_lshl_add_u64 v[148:149], v[148:149], 0, v[146:147]
	v_lshl_add_u64 v[150:151], v[150:151], 0, v[146:147]
	global_load_dwordx4 v[152:155], v[148:149], off
	global_load_dwordx4 v[164:167], v[150:151], off
	v_ashrrev_i32_e32 v157, 31, v156
	s_waitcnt vmcnt(0)
; __device__ __forceinline__ unsigned cvt_pk_bf16(float lo, float hi) { unsigned r; asm volatile("v_cvt_pk_bf16_f32 %0, %1, %2" : "=v"(r) : "v"(lo), "v"(hi)); return r; }
; template <class V> __device__ __forceinline__ void st_wt8(void* p, const V v) { static_assert(sizeof(V) == 8, "8-byte value"); *(V*)p = v; }
; #define EPIIN_LOOP(...) _Pragma("unroll") for (int ai = 0; ai < 2; ++ai) _Pragma("unroll") for (int m = 0; m < 4; ++m) { const int row = row0 + ai * HALF + m * 16, t = row & (seq - 1); (void)t; \
;         _Pragma("unroll") for (int bj = 0; bj < 2; ++bj) { const int within = bj * HALF + wc * 32 + 8 * fq; const f32x4 v0 = acc[ai][bj][m][0], v1 = acc[ai][bj][m][1]; __VA_ARGS__ } }
;     __device__ __forceinline__ void operator()(const f32x4 (&acc)[2][2][4][2], const Unit& u, int wr, int wc, int fr, int fq) const {
;     ...
;         } else if (pn == 11) {
;             EPIIN_LOOP({ const int hd = within >> 5, d = ((within & 31) >> 3) * 4; const f32x4 cc = *(const f32x4*)(rc16 + (size_t)t * 16 + d), ss = *(const f32x4*)(rs16 + (size_t)t * 16 + d);
;                 const f32x4 o1 = (v0 * cc - v1 * ss) * qiscale, o2 = (v1 * cc + v0 * ss) * qiscale; u32x2v w1, w2; w1.x = cvt_pk_bf16(o1[0], o1[1]); w1.y = cvt_pk_bf16(o1[2], o1[3]); w2.x = cvt_pk_bf16(o2[0], o2[1]); w2.y = cvt_pk_bf16(o2[2], o2[3]);
;                 st_wt8(QIB + (size_t)row * 256 + hd * 32 + d, w1); st_wt8(QIB + (size_t)row * 256 + hd * 32 + 16 + d, w2); })
	v_mov_b32_e32 v178, v152
	v_mov_b32_e32 v179, v153
	v_mov_b32_e32 v180, v154
	v_mov_b32_e32 v181, v155
	v_mov_b32_e32 v182, v164
	v_mov_b32_e32 v183, v165
	v_mov_b32_e32 v184, v166
	v_mov_b32_e32 v185, v167
	v_pk_mul_f32 v[168:169], v[76:77], v[166:167]
	v_pk_mul_f32 v[170:171], v[74:75], v[164:165]
	v_pk_mul_f32 v[166:167], v[80:81], v[166:167]
	v_pk_mul_f32 v[164:165], v[78:79], v[164:165]
	v_pk_fma_f32 v[168:169], v[80:81], v[154:155], v[168:169] neg_lo:[0,0,1] neg_hi:[0,0,1]
	v_pk_fma_f32 v[170:171], v[78:79], v[152:153], v[170:171] neg_lo:[0,0,1] neg_hi:[0,0,1]
	v_pk_fma_f32 v[154:155], v[76:77], v[154:155], v[166:167]
	v_pk_fma_f32 v[152:153], v[74:75], v[152:153], v[164:165]
	v_pk_mul_f32 v[154:155], v[154:155], s[44:45] op_sel_hi:[1,0]
	v_pk_mul_f32 v[152:153], v[152:153], s[44:45] op_sel_hi:[1,0]
	v_pk_mul_f32 v[168:169], v[168:169], s[44:45] op_sel_hi:[1,0]
	v_pk_mul_f32 v[170:171], v[170:171], s[44:45] op_sel_hi:[1,0]
	s_nop 0
	v_cvt_pk_bf16_f32 v164, v170, v171
	v_cvt_pk_bf16_f32 v165, v168, v169
	v_cvt_pk_bf16_f32 v152, v152, v153
	v_cvt_pk_bf16_f32 v153, v154, v155
	v_lshlrev_b64 v[154:155], 9, v[156:157]
	v_lshl_add_u64 v[154:155], s[38:39], 0, v[154:155]
	v_lshl_add_u64 v[154:155], v[154:155], 0, v[144:145]
	v_lshl_add_u64 v[156:157], v[154:155], 0, v[214:215]
	global_store_dwordx2 v[156:157], v[164:165], off
	global_store_dwordx2 v[156:157], v[152:153], off offset:32
	v_mov_b32_e32 v152, v178
	v_mov_b32_e32 v153, v179
	v_mov_b32_e32 v154, v180
	v_mov_b32_e32 v155, v181
	s_nop 0
	v_mov_b32_e32 v148, v182
	v_mov_b32_e32 v149, v183
	v_mov_b32_e32 v150, v184
	v_mov_b32_e32 v151, v185
	s_nop 0
	v_pk_mul_f32 v[164:165], v[68:69], v[150:151]
	v_pk_mul_f32 v[166:167], v[66:67], v[148:149]
	v_pk_mul_f32 v[148:149], v[70:71], v[148:149]
	v_pk_fma_f32 v[164:165], v[72:73], v[154:155], v[164:165] neg_lo:[0,0,1] neg_hi:[0,0,1]
	v_pk_fma_f32 v[166:167], v[70:71], v[152:153], v[166:167] neg_lo:[0,0,1] neg_hi:[0,0,1]
	v_pk_mul_f32 v[150:151], v[72:73], v[150:151]
	v_pk_fma_f32 v[148:149], v[66:67], v[152:153], v[148:149]
	v_pk_mul_f32 v[164:165], v[164:165], s[44:45] op_sel_hi:[1,0]
	v_pk_mul_f32 v[166:167], v[166:167], s[44:45] op_sel_hi:[1,0]
	v_pk_fma_f32 v[150:151], v[68:69], v[154:155], v[150:151]
	v_pk_mul_f32 v[148:149], v[148:149], s[44:45] op_sel_hi:[1,0]
	v_cvt_pk_bf16_f32 v152, v166, v167
	v_cvt_pk_bf16_f32 v153, v164, v165
	v_pk_mul_f32 v[150:151], v[150:151], s[44:45] op_sel_hi:[1,0]
	v_cvt_pk_bf16_f32 v148, v148, v149
	s_nop 0
	v_cvt_pk_bf16_f32 v149, v150, v151
	global_store_dwordx2 v[156:157], v[152:153], off offset:256
	global_store_dwordx2 v[156:157], v[148:149], off offset:288
	v_add_u32_e32 v156, 0x80, v142
	v_lshlrev_b32_e32 v143, 6, v156
	v_and_b32_e32 v150, 0x3ffc0, v143
	v_mov_b32_e32 v151, v215
	v_lshl_add_u64 v[148:149], s[22:23], 0, v[150:151]
	v_lshl_add_u64 v[150:151], s[24:25], 0, v[150:151]
	v_lshl_add_u64 v[148:149], v[148:149], 0, v[146:147]
	v_lshl_add_u64 v[150:151], v[150:151], 0, v[146:147]
	global_load_dwordx4 v[152:155], v[148:149], off
	global_load_dwordx4 v[164:167], v[150:151], off
	v_ashrrev_i32_e32 v157, 31, v156
	s_waitcnt vmcnt(0)
	v_mov_b32_e32 v178, v152
	v_mov_b32_e32 v179, v153
	v_mov_b32_e32 v180, v154
	v_mov_b32_e32 v181, v155
	v_mov_b32_e32 v182, v164
	v_mov_b32_e32 v183, v165
	v_mov_b32_e32 v184, v166
	v_mov_b32_e32 v185, v167
	v_pk_mul_f32 v[168:169], v[60:61], v[166:167]
	v_pk_mul_f32 v[170:171], v[58:59], v[164:165]
	v_pk_mul_f32 v[166:167], v[64:65], v[166:167]
	v_pk_mul_f32 v[164:165], v[62:63], v[164:165]
	v_pk_fma_f32 v[168:169], v[64:65], v[154:155], v[168:169] neg_lo:[0,0,1] neg_hi:[0,0,1]
	v_pk_fma_f32 v[170:171], v[62:63], v[152:153], v[170:171] neg_lo:[0,0,1] neg_hi:[0,0,1]
	v_pk_fma_f32 v[154:155], v[60:61], v[154:155], v[166:167]
	v_pk_fma_f32 v[152:153], v[58:59], v[152:153], v[164:165]
	v_pk_mul_f32 v[154:155], v[154:155], s[44:45] op_sel_hi:[1,0]
	v_pk_mul_f32 v[152:153], v[152:153], s[44:45] op_sel_hi:[1,0]
	v_pk_mul_f32 v[168:169], v[168:169], s[44:45] op_sel_hi:[1,0]
	v_pk_mul_f32 v[170:171], v[170:171], s[44:45] op_sel_hi:[1,0]
	s_nop 0
	v_cvt_pk_bf16_f32 v164, v170, v171
	v_cvt_pk_bf16_f32 v165, v168, v169
	v_cvt_pk_bf16_f32 v152, v152, v153
	v_cvt_pk_bf16_f32 v153, v154, v155
	v_lshlrev_b64 v[154:155], 9, v[156:157]
	v_lshl_add_u64 v[154:155], s[38:39], 0, v[154:155]
	v_lshl_add_u64 v[154:155], v[154:155], 0, v[144:145]
	v_lshl_add_u64 v[156:157], v[154:155], 0, v[214:215]
	global_store_dwordx2 v[156:157], v[164:165], off
	global_store_dwordx2 v[156:157], v[152:153], off offset:32
	v_mov_b32_e32 v152, v178
	v_mov_b32_e32 v153, v179
	v_mov_b32_e32 v154, v180
	v_mov_b32_e32 v155, v181
	s_nop 0
	v_mov_b32_e32 v148, v182
	v_mov_b32_e32 v149, v183
	v_mov_b32_e32 v150, v184
	v_mov_b32_e32 v151, v185
	s_nop 0
	v_pk_mul_f32 v[164:165], v[52:53], v[150:151]
	v_pk_mul_f32 v[166:167], v[50:51], v[148:149]
	v_pk_mul_f32 v[148:149], v[54:55], v[148:149]
	v_pk_fma_f32 v[164:165], v[56:57], v[154:155], v[164:165] neg_lo:[0,0,1] neg_hi:[0,0,1]
	v_pk_fma_f32 v[166:167], v[54:55], v[152:153], v[166:167] neg_lo:[0,0,1] neg_hi:[0,0,1]
	v_pk_mul_f32 v[150:151], v[56:57], v[150:151]
	v_pk_fma_f32 v[148:149], v[50:51], v[152:153], v[148:149]
	v_pk_mul_f32 v[164:165], v[164:165], s[44:45] op_sel_hi:[1,0]
	v_pk_mul_f32 v[166:167], v[166:167], s[44:45] op_sel_hi:[1,0]
	v_pk_fma_f32 v[150:151], v[52:53], v[154:155], v[150:151]
	v_pk_mul_f32 v[148:149], v[148:149], s[44:45] op_sel_hi:[1,0]
	v_cvt_pk_bf16_f32 v152, v166, v167
	v_cvt_pk_bf16_f32 v153, v164, v165
	v_pk_mul_f32 v[150:151], v[150:151], s[44:45] op_sel_hi:[1,0]
	v_cvt_pk_bf16_f32 v148, v148, v149
	s_nop 0
	v_cvt_pk_bf16_f32 v149, v150, v151
	global_store_dwordx2 v[156:157], v[152:153], off offset:256
	global_store_dwordx2 v[156:157], v[148:149], off offset:288
	v_add_u32_e32 v156, 0x90, v142
	v_lshlrev_b32_e32 v143, 6, v156
	v_and_b32_e32 v150, 0x3ffc0, v143
	v_mov_b32_e32 v151, v215
	v_lshl_add_u64 v[148:149], s[22:23], 0, v[150:151]
	v_lshl_add_u64 v[150:151], s[24:25], 0, v[150:151]
	v_lshl_add_u64 v[148:149], v[148:149], 0, v[146:147]
	v_lshl_add_u64 v[150:151], v[150:151], 0, v[146:147]
	global_load_dwordx4 v[152:155], v[148:149], off
	global_load_dwordx4 v[164:167], v[150:151], off
	v_ashrrev_i32_e32 v157, 31, v156
	s_waitcnt vmcnt(0)
; __device__ __forceinline__ unsigned cvt_pk_bf16(float lo, float hi) { unsigned r; asm volatile("v_cvt_pk_bf16_f32 %0, %1, %2" : "=v"(r) : "v"(lo), "v"(hi)); return r; }
; template <class V> __device__ __forceinline__ void st_wt8(void* p, const V v) { static_assert(sizeof(V) == 8, "8-byte value"); *(V*)p = v; }
; #define EPIIN_LOOP(...) _Pragma("unroll") for (int ai = 0; ai < 2; ++ai) _Pragma("unroll") for (int m = 0; m < 4; ++m) { const int row = row0 + ai * HALF + m * 16, t = row & (seq - 1); (void)t; \
;         _Pragma("unroll") for (int bj = 0; bj < 2; ++bj) { const int within = bj * HALF + wc * 32 + 8 * fq; const f32x4 v0 = acc[ai][bj][m][0], v1 = acc[ai][bj][m][1]; __VA_ARGS__ } }
;     __device__ __forceinline__ void operator()(const f32x4 (&acc)[2][2][4][2], const Unit& u, int wr, int wc, int fr, int fq) const {
;     ...
;         } else if (pn == 11) {
;             EPIIN_LOOP({ const int hd = within >> 5, d = ((within & 31) >> 3) * 4; const f32x4 cc = *(const f32x4*)(rc16 + (size_t)t * 16 + d), ss = *(const f32x4*)(rs16 + (size_t)t * 16 + d);
;                 const f32x4 o1 = (v0 * cc - v1 * ss) * qiscale, o2 = (v1 * cc + v0 * ss) * qiscale; u32x2v w1, w2; w1.x = cvt_pk_bf16(o1[0], o1[1]); w1.y = cvt_pk_bf16(o1[2], o1[3]); w2.x = cvt_pk_bf16(o2[0], o2[1]); w2.y = cvt_pk_bf16(o2[2], o2[3]);
;                 st_wt8(QIB + (size_t)row * 256 + hd * 32 + d, w1); st_wt8(QIB + (size_t)row * 256 + hd * 32 + 16 + d, w2); })
	v_mov_b32_e32 v178, v152
	v_mov_b32_e32 v179, v153
	v_mov_b32_e32 v180, v154
	v_mov_b32_e32 v181, v155
	v_mov_b32_e32 v182, v164
	v_mov_b32_e32 v183, v165
	v_mov_b32_e32 v184, v166
	v_mov_b32_e32 v185, v167
	v_pk_mul_f32 v[168:169], v[44:45], v[166:167]
	v_pk_mul_f32 v[170:171], v[42:43], v[164:165]
	v_pk_mul_f32 v[166:167], v[48:49], v[166:167]
	v_pk_mul_f32 v[164:165], v[46:47], v[164:165]
	v_pk_fma_f32 v[168:169], v[48:49], v[154:155], v[168:169] neg_lo:[0,0,1] neg_hi:[0,0,1]
	v_pk_fma_f32 v[170:171], v[46:47], v[152:153], v[170:171] neg_lo:[0,0,1] neg_hi:[0,0,1]
	v_pk_fma_f32 v[154:155], v[44:45], v[154:155], v[166:167]
	v_pk_fma_f32 v[152:153], v[42:43], v[152:153], v[164:165]
	v_pk_mul_f32 v[154:155], v[154:155], s[44:45] op_sel_hi:[1,0]
	v_pk_mul_f32 v[152:153], v[152:153], s[44:45] op_sel_hi:[1,0]
	v_pk_mul_f32 v[168:169], v[168:169], s[44:45] op_sel_hi:[1,0]
	v_pk_mul_f32 v[170:171], v[170:171], s[44:45] op_sel_hi:[1,0]
	s_nop 0
	v_cvt_pk_bf16_f32 v164, v170, v171
	v_cvt_pk_bf16_f32 v165, v168, v169
	v_cvt_pk_bf16_f32 v152, v152, v153
	v_cvt_pk_bf16_f32 v153, v154, v155
	v_lshlrev_b64 v[154:155], 9, v[156:157]
	v_lshl_add_u64 v[154:155], s[38:39], 0, v[154:155]
	v_lshl_add_u64 v[154:155], v[154:155], 0, v[144:145]
	v_lshl_add_u64 v[156:157], v[154:155], 0, v[214:215]
	global_store_dwordx2 v[156:157], v[164:165], off
	global_store_dwordx2 v[156:157], v[152:153], off offset:32
	v_mov_b32_e32 v152, v178
	v_mov_b32_e32 v153, v179
	v_mov_b32_e32 v154, v180
	v_mov_b32_e32 v155, v181
	s_nop 0
	v_mov_b32_e32 v148, v182
	v_mov_b32_e32 v149, v183
	v_mov_b32_e32 v150, v184
	v_mov_b32_e32 v151, v185
	s_nop 0
	v_pk_mul_f32 v[164:165], v[36:37], v[150:151]
	v_pk_mul_f32 v[166:167], v[34:35], v[148:149]
	v_pk_mul_f32 v[148:149], v[38:39], v[148:149]
	v_pk_fma_f32 v[164:165], v[40:41], v[154:155], v[164:165] neg_lo:[0,0,1] neg_hi:[0,0,1]
	v_pk_fma_f32 v[166:167], v[38:39], v[152:153], v[166:167] neg_lo:[0,0,1] neg_hi:[0,0,1]
	v_pk_mul_f32 v[150:151], v[40:41], v[150:151]
	v_pk_fma_f32 v[148:149], v[34:35], v[152:153], v[148:149]
	v_pk_mul_f32 v[164:165], v[164:165], s[44:45] op_sel_hi:[1,0]
	v_pk_mul_f32 v[166:167], v[166:167], s[44:45] op_sel_hi:[1,0]
	v_pk_fma_f32 v[150:151], v[36:37], v[154:155], v[150:151]
	v_pk_mul_f32 v[148:149], v[148:149], s[44:45] op_sel_hi:[1,0]
	v_cvt_pk_bf16_f32 v152, v166, v167
	v_cvt_pk_bf16_f32 v153, v164, v165
	v_pk_mul_f32 v[150:151], v[150:151], s[44:45] op_sel_hi:[1,0]
	v_cvt_pk_bf16_f32 v148, v148, v149
	s_nop 0
	v_cvt_pk_bf16_f32 v149, v150, v151
	global_store_dwordx2 v[156:157], v[152:153], off offset:256
	global_store_dwordx2 v[156:157], v[148:149], off offset:288
	v_add_u32_e32 v156, 0xa0, v142
	v_lshlrev_b32_e32 v143, 6, v156
	v_and_b32_e32 v150, 0x3ffc0, v143
	v_mov_b32_e32 v151, v215
	v_lshl_add_u64 v[148:149], s[22:23], 0, v[150:151]
	v_lshl_add_u64 v[150:151], s[24:25], 0, v[150:151]
	v_lshl_add_u64 v[148:149], v[148:149], 0, v[146:147]
	v_lshl_add_u64 v[150:151], v[150:151], 0, v[146:147]
	global_load_dwordx4 v[152:155], v[148:149], off
	global_load_dwordx4 v[164:167], v[150:151], off
	v_ashrrev_i32_e32 v157, 31, v156
	s_waitcnt vmcnt(0)
; __device__ __forceinline__ unsigned cvt_pk_bf16(float lo, float hi) { unsigned r; asm volatile("v_cvt_pk_bf16_f32 %0, %1, %2" : "=v"(r) : "v"(lo), "v"(hi)); return r; }
; template <class V> __device__ __forceinline__ void st_wt8(void* p, const V v) { static_assert(sizeof(V) == 8, "8-byte value"); *(V*)p = v; }
; #define EPIIN_LOOP(...) _Pragma("unroll") for (int ai = 0; ai < 2; ++ai) _Pragma("unroll") for (int m = 0; m < 4; ++m) { const int row = row0 + ai * HALF + m * 16, t = row & (seq - 1); (void)t; \
;         _Pragma("unroll") for (int bj = 0; bj < 2; ++bj) { const int within = bj * HALF + wc * 32 + 8 * fq; const f32x4 v0 = acc[ai][bj][m][0], v1 = acc[ai][bj][m][1]; __VA_ARGS__ } }
;     __device__ __forceinline__ void operator()(const f32x4 (&acc)[2][2][4][2], const Unit& u, int wr, int wc, int fr, int fq) const {
;     ...
;         } else if (pn == 11) {
;             EPIIN_LOOP({ const int hd = within >> 5, d = ((within & 31) >> 3) * 4; const f32x4 cc = *(const f32x4*)(rc16 + (size_t)t * 16 + d), ss = *(const f32x4*)(rs16 + (size_t)t * 16 + d);
;                 const f32x4 o1 = (v0 * cc - v1 * ss) * qiscale, o2 = (v1 * cc + v0 * ss) * qiscale; u32x2v w1, w2; w1.x = cvt_pk_bf16(o1[0], o1[1]); w1.y = cvt_pk_bf16(o1[2], o1[3]); w2.x = cvt_pk_bf16(o2[0], o2[1]); w2.y = cvt_pk_bf16(o2[2], o2[3]);
;                 st_wt8(QIB + (size_t)row * 256 + hd * 32 + d, w1); st_wt8(QIB + (size_t)row * 256 + hd * 32 + 16 + d, w2); })
	v_mov_b32_e32 v178, v152
	v_mov_b32_e32 v179, v153
	v_mov_b32_e32 v180, v154
	v_mov_b32_e32 v181, v155
	v_mov_b32_e32 v182, v164
	v_mov_b32_e32 v183, v165
	v_mov_b32_e32 v184, v166
	v_mov_b32_e32 v185, v167
	v_pk_mul_f32 v[168:169], v[28:29], v[166:167]
	v_pk_mul_f32 v[170:171], v[26:27], v[164:165]
	v_pk_mul_f32 v[166:167], v[32:33], v[166:167]
	v_pk_mul_f32 v[164:165], v[30:31], v[164:165]
	v_pk_fma_f32 v[168:169], v[32:33], v[154:155], v[168:169] neg_lo:[0,0,1] neg_hi:[0,0,1]
	v_pk_fma_f32 v[170:171], v[30:31], v[152:153], v[170:171] neg_lo:[0,0,1] neg_hi:[0,0,1]
	v_pk_fma_f32 v[154:155], v[28:29], v[154:155], v[166:167]
	v_pk_fma_f32 v[152:153], v[26:27], v[152:153], v[164:165]
	v_pk_mul_f32 v[154:155], v[154:155], s[44:45] op_sel_hi:[1,0]
	v_pk_mul_f32 v[152:153], v[152:153], s[44:45] op_sel_hi:[1,0]
	v_pk_mul_f32 v[168:169], v[168:169], s[44:45] op_sel_hi:[1,0]
	v_pk_mul_f32 v[170:171], v[170:171], s[44:45] op_sel_hi:[1,0]
	s_nop 0
	v_cvt_pk_bf16_f32 v164, v170, v171
	v_cvt_pk_bf16_f32 v165, v168, v169
	v_cvt_pk_bf16_f32 v152, v152, v153
	v_cvt_pk_bf16_f32 v153, v154, v155
	v_lshlrev_b64 v[154:155], 9, v[156:157]
	v_lshl_add_u64 v[154:155], s[38:39], 0, v[154:155]
	v_lshl_add_u64 v[154:155], v[154:155], 0, v[144:145]
	v_lshl_add_u64 v[156:157], v[154:155], 0, v[214:215]
	global_store_dwordx2 v[156:157], v[164:165], off
	global_store_dwordx2 v[156:157], v[152:153], off offset:32
	v_mov_b32_e32 v152, v178
	v_mov_b32_e32 v153, v179
	v_mov_b32_e32 v154, v180
	v_mov_b32_e32 v155, v181
	s_nop 0
	v_mov_b32_e32 v148, v182
	v_mov_b32_e32 v149, v183
	v_mov_b32_e32 v150, v184
	v_mov_b32_e32 v151, v185
	s_nop 0
	v_pk_mul_f32 v[164:165], v[20:21], v[150:151]
	v_pk_mul_f32 v[166:167], v[18:19], v[148:149]
	v_pk_fma_f32 v[164:165], v[24:25], v[154:155], v[164:165] neg_lo:[0,0,1] neg_hi:[0,0,1]
	v_pk_fma_f32 v[166:167], v[22:23], v[152:153], v[166:167] neg_lo:[0,0,1] neg_hi:[0,0,1]
	v_pk_mul_f32 v[164:165], v[164:165], s[44:45] op_sel_hi:[1,0]
	v_pk_mul_f32 v[148:149], v[22:23], v[148:149]
	v_pk_mul_f32 v[166:167], v[166:167], s[44:45] op_sel_hi:[1,0]
	v_pk_mul_f32 v[150:151], v[24:25], v[150:151]
	v_pk_fma_f32 v[148:149], v[18:19], v[152:153], v[148:149]
	v_cvt_pk_bf16_f32 v152, v166, v167
	v_cvt_pk_bf16_f32 v153, v164, v165
	v_add_u32_e32 v164, 0xb0, v142
	v_pk_fma_f32 v[150:151], v[20:21], v[154:155], v[150:151]
	v_pk_mul_f32 v[148:149], v[148:149], s[44:45] op_sel_hi:[1,0]
	v_lshlrev_b32_e32 v143, 6, v164
	v_pk_mul_f32 v[150:151], v[150:151], s[44:45] op_sel_hi:[1,0]
	v_cvt_pk_bf16_f32 v148, v148, v149
	v_and_b32_e32 v154, 0x3ffc0, v143
	v_cvt_pk_bf16_f32 v149, v150, v151
	v_mov_b32_e32 v155, v215
	global_store_dwordx2 v[156:157], v[152:153], off offset:256
	global_store_dwordx2 v[156:157], v[148:149], off offset:288
	v_lshl_add_u64 v[148:149], s[22:23], 0, v[154:155]
	v_lshl_add_u64 v[154:155], s[24:25], 0, v[154:155]
	v_lshl_add_u64 v[148:149], v[148:149], 0, v[146:147]
	v_lshl_add_u64 v[146:147], v[154:155], 0, v[146:147]
	global_load_dwordx4 v[150:153], v[148:149], off
	global_load_dwordx4 v[154:157], v[146:147], off
	v_ashrrev_i32_e32 v165, 31, v164
	s_mov_b64 s[22:23], 0
	s_waitcnt vmcnt(0)
	v_mov_b32_e32 v178, v150
	v_mov_b32_e32 v179, v151
	v_mov_b32_e32 v180, v152
	v_mov_b32_e32 v181, v153
	v_mov_b32_e32 v182, v154
	v_mov_b32_e32 v183, v155
	v_mov_b32_e32 v184, v156
	v_mov_b32_e32 v185, v157
	v_pk_mul_f32 v[166:167], v[12:13], v[156:157]
	v_pk_mul_f32 v[168:169], v[10:11], v[154:155]
	v_pk_mul_f32 v[156:157], v[16:17], v[156:157]
	v_pk_mul_f32 v[154:155], v[14:15], v[154:155]
	v_pk_fma_f32 v[166:167], v[16:17], v[152:153], v[166:167] neg_lo:[0,0,1] neg_hi:[0,0,1]
	v_pk_fma_f32 v[168:169], v[14:15], v[150:151], v[168:169] neg_lo:[0,0,1] neg_hi:[0,0,1]
	v_pk_fma_f32 v[152:153], v[12:13], v[152:153], v[156:157]
	v_pk_fma_f32 v[150:151], v[10:11], v[150:151], v[154:155]
	v_pk_mul_f32 v[152:153], v[152:153], s[44:45] op_sel_hi:[1,0]
	v_pk_mul_f32 v[150:151], v[150:151], s[44:45] op_sel_hi:[1,0]
	v_pk_mul_f32 v[166:167], v[166:167], s[44:45] op_sel_hi:[1,0]
	v_pk_mul_f32 v[168:169], v[168:169], s[44:45] op_sel_hi:[1,0]
	s_nop 0
	v_cvt_pk_bf16_f32 v154, v168, v169
	v_cvt_pk_bf16_f32 v155, v166, v167
	v_cvt_pk_bf16_f32 v150, v150, v151
	v_cvt_pk_bf16_f32 v151, v152, v153
	v_lshlrev_b64 v[152:153], 9, v[164:165]
	v_lshl_add_u64 v[152:153], s[38:39], 0, v[152:153]
	v_lshl_add_u64 v[144:145], v[152:153], 0, v[144:145]
	v_lshl_add_u64 v[152:153], v[144:145], 0, v[214:215]
	global_store_dwordx2 v[152:153], v[154:155], off
	global_store_dwordx2 v[152:153], v[150:151], off offset:32
	v_mov_b32_e32 v148, v178
	v_mov_b32_e32 v149, v179
	v_mov_b32_e32 v150, v180
	v_mov_b32_e32 v151, v181
	s_nop 0
	v_mov_b32_e32 v144, v182
	v_mov_b32_e32 v145, v183
	v_mov_b32_e32 v146, v184
	v_mov_b32_e32 v147, v185
	s_nop 0
	v_pk_mul_f32 v[154:155], v[4:5], v[146:147]
	v_pk_mul_f32 v[156:157], v[2:3], v[144:145]
	v_pk_mul_f32 v[144:145], v[6:7], v[144:145]
	v_pk_fma_f32 v[154:155], v[8:9], v[150:151], v[154:155] neg_lo:[0,0,1] neg_hi:[0,0,1]
	v_pk_fma_f32 v[156:157], v[6:7], v[148:149], v[156:157] neg_lo:[0,0,1] neg_hi:[0,0,1]
	v_pk_mul_f32 v[146:147], v[8:9], v[146:147]
	v_pk_fma_f32 v[144:145], v[2:3], v[148:149], v[144:145]
	v_pk_mul_f32 v[154:155], v[154:155], s[44:45] op_sel_hi:[1,0]
	v_pk_mul_f32 v[156:157], v[156:157], s[44:45] op_sel_hi:[1,0]
	v_pk_fma_f32 v[146:147], v[4:5], v[150:151], v[146:147]
	v_pk_mul_f32 v[144:145], v[144:145], s[44:45] op_sel_hi:[1,0]
	v_cvt_pk_bf16_f32 v148, v156, v157
	v_cvt_pk_bf16_f32 v149, v154, v155
	v_pk_mul_f32 v[146:147], v[146:147], s[44:45] op_sel_hi:[1,0]
	v_cvt_pk_bf16_f32 v144, v144, v145
	s_nop 0
	v_cvt_pk_bf16_f32 v145, v146, v147
	global_store_dwordx2 v[152:153], v[148:149], off offset:256
	global_store_dwordx2 v[152:153], v[144:145], off offset:288

; __device__ __forceinline__ unsigned cvt_pk_bf16(float lo, float hi) { unsigned r; asm volatile("v_cvt_pk_bf16_f32 %0, %1, %2" : "=v"(r) : "v"(lo), "v"(hi)); return r; }
; template <class V> __device__ __forceinline__ void st_wt8(void* p, const V v) { static_assert(sizeof(V) == 8, "8-byte value"); *(V*)p = v; }
; #define EPIIN_LOOP(...) _Pragma("unroll") for (int ai = 0; ai < 2; ++ai) _Pragma("unroll") for (int m = 0; m < 4; ++m) { const int row = row0 + ai * HALF + m * 16, t = row & (seq - 1); (void)t; \
;         _Pragma("unroll") for (int bj = 0; bj < 2; ++bj) { const int within = bj * HALF + wc * 32 + 8 * fq; const f32x4 v0 = acc[ai][bj][m][0], v1 = acc[ai][bj][m][1]; __VA_ARGS__ } }
;     __device__ __forceinline__ void operator()(const f32x4 (&acc)[2][2][4][2], const Unit& u, int wr, int wc, int fr, int fq) const {
;     ...
;         } else { const int hbase = (pn - 7) * 4;
;             EPIIN_LOOP({ const int hd = within >> 6, d = ((within & 63) >> 3) * 4; const f32x4 cc = *(const f32x4*)(rc + (size_t)t * 32 + d), ss = *(const f32x4*)(rs + (size_t)t * 32 + d);
;                 const f32x4 o1 = (v0 * cc - v1 * ss) * qscale, o2 = (v1 * cc + v0 * ss) * qscale;
;                 u32x2v w1, w2; w1.x = cvt_pk_bf16(o1[0], o1[1]); w1.y = cvt_pk_bf16(o1[2], o1[3]); w2.x = cvt_pk_bf16(o2[0], o2[1]); w2.y = cvt_pk_bf16(o2[2], o2[3]);
;                 bf16_t* dst = AQB + (size_t)row * 512 + (hbase + hd) * 64 + d; st_wt8(dst, w1); st_wt8(dst + 32, w2); })
.LBB0_358:
	v_lshl_add_u32 v163, v162, 3, s31
	v_ashrrev_i32_e32 v143, 31, v142
	v_lshlrev_b64 v[164:165], 10, v[142:143]
	v_lshrrev_b32_e32 v143, 1, v163
	v_readlane_b32 s40, v249, 4
	v_readlane_b32 s22, v250, 23
	v_and_b32_e32 v143, 28, v143
	v_readlane_b32 s42, v249, 6
	v_readlane_b32 s43, v249, 7
	v_readlane_b32 s23, v250, 24
	v_lshlrev_b32_e32 v148, 2, v143
	v_lshl_add_u64 v[144:145], s[42:43], 0, v[214:215]
	v_mov_b32_e32 v149, v215
	v_lshl_add_u64 v[152:153], s[22:23], 0, v[214:215]
	v_lshl_add_u64 v[150:151], v[144:145], 0, v[148:149]
	v_lshl_add_u64 v[152:153], v[152:153], 0, v[148:149]
	global_load_dwordx4 v[144:147], v[150:151], off
	global_load_dwordx4 v[154:157], v[152:153], off
	s_lshl_b32 s2, s37, 8
	s_mov_b32 s38, 0x3e38aa3b
	s_addk_i32 s2, 0xf900
	v_readlane_b32 s24, v250, 37
	v_readlane_b32 s25, v250, 38
	v_readlane_b32 s41, v249, 5
	s_mov_b32 s40, 0xf800000
	s_waitcnt vmcnt(0)
	v_mov_b32_e32 v178, v144
	v_mov_b32_e32 v179, v145
	v_mov_b32_e32 v180, v146
	v_mov_b32_e32 v181, v147
	v_mov_b32_e32 v182, v154
	v_mov_b32_e32 v183, v155
	v_mov_b32_e32 v184, v156
	v_mov_b32_e32 v185, v157
	v_pk_mul_f32 v[168:169], v[122:123], v[154:155]
	v_pk_mul_f32 v[154:155], v[126:127], v[154:155]
	v_pk_mul_f32 v[166:167], v[124:125], v[156:157]
	v_pk_fma_f32 v[168:169], v[126:127], v[144:145], v[168:169] neg_lo:[0,0,1] neg_hi:[0,0,1]
	v_pk_fma_f32 v[144:145], v[122:123], v[144:145], v[154:155]
	v_pk_fma_f32 v[166:167], v[128:129], v[146:147], v[166:167] neg_lo:[0,0,1] neg_hi:[0,0,1]
	v_pk_mul_f32 v[156:157], v[128:129], v[156:157]
	v_pk_mul_f32 v[144:145], v[144:145], s[38:39] op_sel_hi:[1,0]
	v_pk_mul_f32 v[166:167], v[166:167], s[38:39] op_sel_hi:[1,0]
	v_pk_mul_f32 v[168:169], v[168:169], s[38:39] op_sel_hi:[1,0]
	v_pk_fma_f32 v[146:147], v[124:125], v[146:147], v[156:157]
	v_cvt_pk_bf16_f32 v154, v168, v169
	v_cvt_pk_bf16_f32 v155, v166, v167
	v_cvt_pk_bf16_f32 v156, v144, v145
	v_add_u32_e32 v144, s2, v163
	v_and_b32_e32 v144, 0xffffffc0, v144
	v_pk_mul_f32 v[146:147], v[146:147], s[38:39] op_sel_hi:[1,0]
	v_ashrrev_i32_e32 v145, 31, v144
	v_cvt_pk_bf16_f32 v157, v146, v147
	v_lshl_add_u64 v[146:147], s[24:25], 0, v[164:165]
	v_lshlrev_b64 v[144:145], 1, v[144:145]
	v_lshl_add_u64 v[164:165], v[146:147], 0, v[144:145]
	v_lshlrev_b32_e32 v146, 1, v143
	v_mov_b32_e32 v147, v215
	v_lshl_add_u64 v[164:165], v[164:165], 0, v[146:147]
	global_store_dwordx2 v[164:165], v[154:155], off
	global_store_dwordx2 v[164:165], v[156:157], off offset:64
	v_mov_b32_e32 v154, v178
	v_mov_b32_e32 v155, v179
	v_mov_b32_e32 v156, v180
	v_mov_b32_e32 v157, v181
	s_nop 0
	v_mov_b32_e32 v150, v182
	v_mov_b32_e32 v151, v183
	v_mov_b32_e32 v152, v184
	v_mov_b32_e32 v153, v185
	s_nop 0
	v_pk_mul_f32 v[168:169], v[114:115], v[150:151]
	v_pk_mul_f32 v[150:151], v[118:119], v[150:151]
	v_pk_mul_f32 v[166:167], v[116:117], v[152:153]
	v_pk_fma_f32 v[150:151], v[114:115], v[154:155], v[150:151]
	v_pk_fma_f32 v[166:167], v[120:121], v[156:157], v[166:167] neg_lo:[0,0,1] neg_hi:[0,0,1]
	v_pk_fma_f32 v[168:169], v[118:119], v[154:155], v[168:169] neg_lo:[0,0,1] neg_hi:[0,0,1]
	v_pk_mul_f32 v[152:153], v[120:121], v[152:153]
	v_pk_mul_f32 v[150:151], v[150:151], s[38:39] op_sel_hi:[1,0]
	v_pk_mul_f32 v[166:167], v[166:167], s[38:39] op_sel_hi:[1,0]
	v_pk_mul_f32 v[168:169], v[168:169], s[38:39] op_sel_hi:[1,0]
	v_pk_fma_f32 v[152:153], v[116:117], v[156:157], v[152:153]
	v_cvt_pk_bf16_f32 v154, v168, v169
	v_cvt_pk_bf16_f32 v155, v166, v167
	v_cvt_pk_bf16_f32 v150, v150, v151
	s_nop 0
	v_pk_mul_f32 v[152:153], v[152:153], s[38:39] op_sel_hi:[1,0]
	s_nop 0
	v_cvt_pk_bf16_f32 v151, v152, v153
	global_store_dwordx2 v[164:165], v[154:155], off offset:256
	global_store_dwordx2 v[164:165], v[150:151], off offset:320
	v_add_u32_e32 v150, 16, v142
	v_lshlrev_b32_e32 v143, 7, v150
	v_ashrrev_i32_e32 v151, 31, v150
	v_and_b32_e32 v152, 0x7ff80, v143
	v_mov_b32_e32 v153, v215
	v_lshlrev_b64 v[168:169], 10, v[150:151]
	v_lshl_add_u64 v[150:151], s[42:43], 0, v[152:153]
	v_lshl_add_u64 v[152:153], s[22:23], 0, v[152:153]
	v_lshl_add_u64 v[150:151], v[150:151], 0, v[148:149]
	v_lshl_add_u64 v[152:153], v[152:153], 0, v[148:149]
	global_load_dwordx4 v[154:157], v[150:151], off
	global_load_dwordx4 v[164:167], v[152:153], off
	s_waitcnt vmcnt(0)
; __device__ __forceinline__ unsigned cvt_pk_bf16(float lo, float hi) { unsigned r; asm volatile("v_cvt_pk_bf16_f32 %0, %1, %2" : "=v"(r) : "v"(lo), "v"(hi)); return r; }
; template <class V> __device__ __forceinline__ void st_wt8(void* p, const V v) { static_assert(sizeof(V) == 8, "8-byte value"); *(V*)p = v; }
; #define EPIIN_LOOP(...) _Pragma("unroll") for (int ai = 0; ai < 2; ++ai) _Pragma("unroll") for (int m = 0; m < 4; ++m) { const int row = row0 + ai * HALF + m * 16, t = row & (seq - 1); (void)t; \
;         _Pragma("unroll") for (int bj = 0; bj < 2; ++bj) { const int within = bj * HALF + wc * 32 + 8 * fq; const f32x4 v0 = acc[ai][bj][m][0], v1 = acc[ai][bj][m][1]; __VA_ARGS__ } }
;     __device__ __forceinline__ void operator()(const f32x4 (&acc)[2][2][4][2], const Unit& u, int wr, int wc, int fr, int fq) const {
;     ...
;         } else { const int hbase = (pn - 7) * 4;
;             EPIIN_LOOP({ const int hd = within >> 6, d = ((within & 63) >> 3) * 4; const f32x4 cc = *(const f32x4*)(rc + (size_t)t * 32 + d), ss = *(const f32x4*)(rs + (size_t)t * 32 + d);
;                 const f32x4 o1 = (v0 * cc - v1 * ss) * qscale, o2 = (v1 * cc + v0 * ss) * qscale;
;                 u32x2v w1, w2; w1.x = cvt_pk_bf16(o1[0], o1[1]); w1.y = cvt_pk_bf16(o1[2], o1[3]); w2.x = cvt_pk_bf16(o2[0], o2[1]); w2.y = cvt_pk_bf16(o2[2], o2[3]);
;                 bf16_t* dst = AQB + (size_t)row * 512 + (hbase + hd) * 64 + d; st_wt8(dst, w1); st_wt8(dst + 32, w2); })
	v_mov_b32_e32 v178, v154
	v_mov_b32_e32 v179, v155
	v_mov_b32_e32 v180, v156
	v_mov_b32_e32 v181, v157
	v_mov_b32_e32 v182, v164
	v_mov_b32_e32 v183, v165
	v_mov_b32_e32 v184, v166
	v_mov_b32_e32 v185, v167
	v_pk_mul_f32 v[170:171], v[108:109], v[166:167]
	v_pk_mul_f32 v[172:173], v[106:107], v[164:165]
	v_pk_mul_f32 v[166:167], v[112:113], v[166:167]
	v_pk_mul_f32 v[164:165], v[110:111], v[164:165]
	v_pk_fma_f32 v[170:171], v[112:113], v[156:157], v[170:171] neg_lo:[0,0,1] neg_hi:[0,0,1]
	v_pk_fma_f32 v[172:173], v[110:111], v[154:155], v[172:173] neg_lo:[0,0,1] neg_hi:[0,0,1]
	v_pk_fma_f32 v[156:157], v[108:109], v[156:157], v[166:167]
	v_pk_fma_f32 v[154:155], v[106:107], v[154:155], v[164:165]
	v_pk_mul_f32 v[156:157], v[156:157], s[38:39] op_sel_hi:[1,0]
	v_pk_mul_f32 v[154:155], v[154:155], s[38:39] op_sel_hi:[1,0]
	v_pk_mul_f32 v[170:171], v[170:171], s[38:39] op_sel_hi:[1,0]
	v_pk_mul_f32 v[172:173], v[172:173], s[38:39] op_sel_hi:[1,0]
	s_nop 0
	v_cvt_pk_bf16_f32 v164, v172, v173
	v_cvt_pk_bf16_f32 v165, v170, v171
	v_cvt_pk_bf16_f32 v154, v154, v155
	v_cvt_pk_bf16_f32 v155, v156, v157
	v_lshl_add_u64 v[156:157], s[24:25], 0, v[168:169]
	v_lshl_add_u64 v[156:157], v[156:157], 0, v[144:145]
	v_lshl_add_u64 v[166:167], v[156:157], 0, v[146:147]
	global_store_dwordx2 v[166:167], v[164:165], off
	global_store_dwordx2 v[166:167], v[154:155], off offset:64
	v_mov_b32_e32 v154, v178
	v_mov_b32_e32 v155, v179
	v_mov_b32_e32 v156, v180
	v_mov_b32_e32 v157, v181
	s_nop 0
	v_mov_b32_e32 v150, v182
	v_mov_b32_e32 v151, v183
	v_mov_b32_e32 v152, v184
	v_mov_b32_e32 v153, v185
	s_nop 0
	v_pk_mul_f32 v[168:169], v[98:99], v[150:151]
	v_pk_mul_f32 v[150:151], v[102:103], v[150:151]
	v_pk_mul_f32 v[164:165], v[100:101], v[152:153]
	v_pk_fma_f32 v[150:151], v[98:99], v[154:155], v[150:151]
	v_pk_fma_f32 v[164:165], v[104:105], v[156:157], v[164:165] neg_lo:[0,0,1] neg_hi:[0,0,1]
	v_pk_fma_f32 v[168:169], v[102:103], v[154:155], v[168:169] neg_lo:[0,0,1] neg_hi:[0,0,1]
	v_pk_mul_f32 v[152:153], v[104:105], v[152:153]
	v_pk_mul_f32 v[150:151], v[150:151], s[38:39] op_sel_hi:[1,0]
	v_pk_mul_f32 v[164:165], v[164:165], s[38:39] op_sel_hi:[1,0]
	v_pk_mul_f32 v[168:169], v[168:169], s[38:39] op_sel_hi:[1,0]
	v_pk_fma_f32 v[152:153], v[100:101], v[156:157], v[152:153]
	v_cvt_pk_bf16_f32 v154, v168, v169
	v_cvt_pk_bf16_f32 v155, v164, v165
	v_cvt_pk_bf16_f32 v150, v150, v151
	s_nop 0
	v_pk_mul_f32 v[152:153], v[152:153], s[38:39] op_sel_hi:[1,0]
	s_nop 0
	v_cvt_pk_bf16_f32 v151, v152, v153
	global_store_dwordx2 v[166:167], v[154:155], off offset:256
	global_store_dwordx2 v[166:167], v[150:151], off offset:320
	v_add_u32_e32 v150, 32, v142
	v_lshlrev_b32_e32 v143, 7, v150
	v_ashrrev_i32_e32 v151, 31, v150
	v_and_b32_e32 v152, 0x7ff80, v143
	v_mov_b32_e32 v153, v215
	v_lshlrev_b64 v[168:169], 10, v[150:151]
	v_lshl_add_u64 v[150:151], s[42:43], 0, v[152:153]
	v_lshl_add_u64 v[152:153], s[22:23], 0, v[152:153]
	v_lshl_add_u64 v[150:151], v[150:151], 0, v[148:149]
	v_lshl_add_u64 v[152:153], v[152:153], 0, v[148:149]
	global_load_dwordx4 v[154:157], v[150:151], off
	global_load_dwordx4 v[164:167], v[152:153], off
	s_waitcnt vmcnt(0)
	v_mov_b32_e32 v178, v154
	v_mov_b32_e32 v179, v155
	v_mov_b32_e32 v180, v156
	v_mov_b32_e32 v181, v157
	v_mov_b32_e32 v182, v164
	v_mov_b32_e32 v183, v165
	v_mov_b32_e32 v184, v166
	v_mov_b32_e32 v185, v167
	v_pk_mul_f32 v[170:171], v[92:93], v[166:167]
	v_pk_mul_f32 v[172:173], v[90:91], v[164:165]
	v_pk_mul_f32 v[166:167], v[96:97], v[166:167]
	v_pk_mul_f32 v[164:165], v[94:95], v[164:165]
	v_pk_fma_f32 v[170:171], v[96:97], v[156:157], v[170:171] neg_lo:[0,0,1] neg_hi:[0,0,1]
	v_pk_fma_f32 v[172:173], v[94:95], v[154:155], v[172:173] neg_lo:[0,0,1] neg_hi:[0,0,1]
	v_pk_fma_f32 v[156:157], v[92:93], v[156:157], v[166:167]
	v_pk_fma_f32 v[154:155], v[90:91], v[154:155], v[164:165]
	v_pk_mul_f32 v[156:157], v[156:157], s[38:39] op_sel_hi:[1,0]
	v_pk_mul_f32 v[154:155], v[154:155], s[38:39] op_sel_hi:[1,0]
	v_pk_mul_f32 v[170:171], v[170:171], s[38:39] op_sel_hi:[1,0]
	v_pk_mul_f32 v[172:173], v[172:173], s[38:39] op_sel_hi:[1,0]
	s_nop 0
	v_cvt_pk_bf16_f32 v164, v172, v173
	v_cvt_pk_bf16_f32 v165, v170, v171
	v_cvt_pk_bf16_f32 v154, v154, v155
	v_cvt_pk_bf16_f32 v155, v156, v157
	v_lshl_add_u64 v[156:157], s[24:25], 0, v[168:169]
	v_lshl_add_u64 v[156:157], v[156:157], 0, v[144:145]
	v_lshl_add_u64 v[166:167], v[156:157], 0, v[146:147]
	global_store_dwordx2 v[166:167], v[164:165], off
	global_store_dwordx2 v[166:167], v[154:155], off offset:64
	v_mov_b32_e32 v154, v178
	v_mov_b32_e32 v155, v179
	v_mov_b32_e32 v156, v180
	v_mov_b32_e32 v157, v181
	s_nop 0
	v_mov_b32_e32 v150, v182
	v_mov_b32_e32 v151, v183
	v_mov_b32_e32 v152, v184
	v_mov_b32_e32 v153, v185
	s_nop 0
	v_pk_mul_f32 v[168:169], v[82:83], v[150:151]
	v_pk_mul_f32 v[150:151], v[86:87], v[150:151]
	v_pk_mul_f32 v[164:165], v[84:85], v[152:153]
	v_pk_fma_f32 v[150:151], v[82:83], v[154:155], v[150:151]
	v_pk_fma_f32 v[164:165], v[88:89], v[156:157], v[164:165] neg_lo:[0,0,1] neg_hi:[0,0,1]
	v_pk_fma_f32 v[168:169], v[86:87], v[154:155], v[168:169] neg_lo:[0,0,1] neg_hi:[0,0,1]
	v_pk_mul_f32 v[152:153], v[88:89], v[152:153]
	v_pk_mul_f32 v[150:151], v[150:151], s[38:39] op_sel_hi:[1,0]
	v_pk_mul_f32 v[164:165], v[164:165], s[38:39] op_sel_hi:[1,0]
	v_pk_mul_f32 v[168:169], v[168:169], s[38:39] op_sel_hi:[1,0]
	v_pk_fma_f32 v[152:153], v[84:85], v[156:157], v[152:153]
	v_cvt_pk_bf16_f32 v154, v168, v169
	v_cvt_pk_bf16_f32 v155, v164, v165
	v_cvt_pk_bf16_f32 v150, v150, v151
	s_nop 0
	v_pk_mul_f32 v[152:153], v[152:153], s[38:39] op_sel_hi:[1,0]
	s_nop 0
	v_cvt_pk_bf16_f32 v151, v152, v153
	global_store_dwordx2 v[166:167], v[154:155], off offset:256
	global_store_dwordx2 v[166:167], v[150:151], off offset:320
	v_add_u32_e32 v150, 48, v142
	v_lshlrev_b32_e32 v143, 7, v150
	v_ashrrev_i32_e32 v151, 31, v150
	v_and_b32_e32 v152, 0x7ff80, v143
	v_mov_b32_e32 v153, v215
	v_lshlrev_b64 v[168:169], 10, v[150:151]
	v_lshl_add_u64 v[150:151], s[42:43], 0, v[152:153]
	v_lshl_add_u64 v[152:153], s[22:23], 0, v[152:153]
	v_lshl_add_u64 v[150:151], v[150:151], 0, v[148:149]
	v_lshl_add_u64 v[152:153], v[152:153], 0, v[148:149]
	global_load_dwordx4 v[154:157], v[150:151], off
	global_load_dwordx4 v[164:167], v[152:153], off
	s_waitcnt vmcnt(0)
; __device__ __forceinline__ unsigned cvt_pk_bf16(float lo, float hi) { unsigned r; asm volatile("v_cvt_pk_bf16_f32 %0, %1, %2" : "=v"(r) : "v"(lo), "v"(hi)); return r; }
; template <class V> __device__ __forceinline__ void st_wt8(void* p, const V v) { static_assert(sizeof(V) == 8, "8-byte value"); *(V*)p = v; }
; #define EPIIN_LOOP(...) _Pragma("unroll") for (int ai = 0; ai < 2; ++ai) _Pragma("unroll") for (int m = 0; m < 4; ++m) { const int row = row0 + ai * HALF + m * 16, t = row & (seq - 1); (void)t; \
;         _Pragma("unroll") for (int bj = 0; bj < 2; ++bj) { const int within = bj * HALF + wc * 32 + 8 * fq; const f32x4 v0 = acc[ai][bj][m][0], v1 = acc[ai][bj][m][1]; __VA_ARGS__ } }
;     __device__ __forceinline__ void operator()(const f32x4 (&acc)[2][2][4][2], const Unit& u, int wr, int wc, int fr, int fq) const {
;     ...
;         } else { const int hbase = (pn - 7) * 4;
;             EPIIN_LOOP({ const int hd = within >> 6, d = ((within & 63) >> 3) * 4; const f32x4 cc = *(const f32x4*)(rc + (size_t)t * 32 + d), ss = *(const f32x4*)(rs + (size_t)t * 32 + d);
;                 const f32x4 o1 = (v0 * cc - v1 * ss) * qscale, o2 = (v1 * cc + v0 * ss) * qscale;
;                 u32x2v w1, w2; w1.x = cvt_pk_bf16(o1[0], o1[1]); w1.y = cvt_pk_bf16(o1[2], o1[3]); w2.x = cvt_pk_bf16(o2[0], o2[1]); w2.y = cvt_pk_bf16(o2[2], o2[3]);
;                 bf16_t* dst = AQB + (size_t)row * 512 + (hbase + hd) * 64 + d; st_wt8(dst, w1); st_wt8(dst + 32, w2); })
	v_mov_b32_e32 v178, v154
	v_mov_b32_e32 v179, v155
	v_mov_b32_e32 v180, v156
	v_mov_b32_e32 v181, v157
	v_mov_b32_e32 v182, v164
	v_mov_b32_e32 v183, v165
	v_mov_b32_e32 v184, v166
	v_mov_b32_e32 v185, v167
	v_pk_mul_f32 v[170:171], v[76:77], v[166:167]
	v_pk_mul_f32 v[172:173], v[74:75], v[164:165]
	v_pk_mul_f32 v[166:167], v[80:81], v[166:167]
	v_pk_mul_f32 v[164:165], v[78:79], v[164:165]
	v_pk_fma_f32 v[170:171], v[80:81], v[156:157], v[170:171] neg_lo:[0,0,1] neg_hi:[0,0,1]
	v_pk_fma_f32 v[172:173], v[78:79], v[154:155], v[172:173] neg_lo:[0,0,1] neg_hi:[0,0,1]
	v_pk_fma_f32 v[156:157], v[76:77], v[156:157], v[166:167]
	v_pk_fma_f32 v[154:155], v[74:75], v[154:155], v[164:165]
	v_pk_mul_f32 v[156:157], v[156:157], s[38:39] op_sel_hi:[1,0]
	v_pk_mul_f32 v[154:155], v[154:155], s[38:39] op_sel_hi:[1,0]
	v_pk_mul_f32 v[170:171], v[170:171], s[38:39] op_sel_hi:[1,0]
	v_pk_mul_f32 v[172:173], v[172:173], s[38:39] op_sel_hi:[1,0]
	s_nop 0
	v_cvt_pk_bf16_f32 v164, v172, v173
	v_cvt_pk_bf16_f32 v165, v170, v171
	v_cvt_pk_bf16_f32 v154, v154, v155
	v_cvt_pk_bf16_f32 v155, v156, v157
	v_lshl_add_u64 v[156:157], s[24:25], 0, v[168:169]
	v_lshl_add_u64 v[156:157], v[156:157], 0, v[144:145]
	v_lshl_add_u64 v[166:167], v[156:157], 0, v[146:147]
	global_store_dwordx2 v[166:167], v[164:165], off
	global_store_dwordx2 v[166:167], v[154:155], off offset:64
	v_mov_b32_e32 v154, v178
	v_mov_b32_e32 v155, v179
	v_mov_b32_e32 v156, v180
	v_mov_b32_e32 v157, v181
	s_nop 0
	v_mov_b32_e32 v150, v182
	v_mov_b32_e32 v151, v183
	v_mov_b32_e32 v152, v184
	v_mov_b32_e32 v153, v185
	s_nop 0
	v_pk_mul_f32 v[168:169], v[66:67], v[150:151]
	v_pk_mul_f32 v[150:151], v[70:71], v[150:151]
	v_pk_mul_f32 v[164:165], v[68:69], v[152:153]
	v_pk_fma_f32 v[150:151], v[66:67], v[154:155], v[150:151]
	v_pk_fma_f32 v[164:165], v[72:73], v[156:157], v[164:165] neg_lo:[0,0,1] neg_hi:[0,0,1]
	v_pk_fma_f32 v[168:169], v[70:71], v[154:155], v[168:169] neg_lo:[0,0,1] neg_hi:[0,0,1]
	v_pk_mul_f32 v[152:153], v[72:73], v[152:153]
	v_pk_mul_f32 v[150:151], v[150:151], s[38:39] op_sel_hi:[1,0]
	v_pk_mul_f32 v[164:165], v[164:165], s[38:39] op_sel_hi:[1,0]
	v_pk_mul_f32 v[168:169], v[168:169], s[38:39] op_sel_hi:[1,0]
	v_pk_fma_f32 v[152:153], v[68:69], v[156:157], v[152:153]
	v_cvt_pk_bf16_f32 v154, v168, v169
	v_cvt_pk_bf16_f32 v155, v164, v165
	v_cvt_pk_bf16_f32 v150, v150, v151
	s_nop 0
	v_pk_mul_f32 v[152:153], v[152:153], s[38:39] op_sel_hi:[1,0]
	s_nop 0
	v_cvt_pk_bf16_f32 v151, v152, v153
	global_store_dwordx2 v[166:167], v[154:155], off offset:256
	global_store_dwordx2 v[166:167], v[150:151], off offset:320
	v_add_u32_e32 v150, 0x80, v142
	v_lshlrev_b32_e32 v143, 7, v150
	v_ashrrev_i32_e32 v151, 31, v150
	v_and_b32_e32 v152, 0x7ff80, v143
	v_mov_b32_e32 v153, v215
	v_lshlrev_b64 v[168:169], 10, v[150:151]
	v_lshl_add_u64 v[150:151], s[42:43], 0, v[152:153]
	v_lshl_add_u64 v[152:153], s[22:23], 0, v[152:153]
	v_lshl_add_u64 v[150:151], v[150:151], 0, v[148:149]
	v_lshl_add_u64 v[152:153], v[152:153], 0, v[148:149]
	global_load_dwordx4 v[154:157], v[150:151], off
	global_load_dwordx4 v[164:167], v[152:153], off
	s_waitcnt vmcnt(0)
	v_mov_b32_e32 v178, v154
	v_mov_b32_e32 v179, v155
	v_mov_b32_e32 v180, v156
	v_mov_b32_e32 v181, v157
	v_mov_b32_e32 v182, v164
	v_mov_b32_e32 v183, v165
	v_mov_b32_e32 v184, v166
	v_mov_b32_e32 v185, v167
	v_pk_mul_f32 v[170:171], v[60:61], v[166:167]
	v_pk_mul_f32 v[172:173], v[58:59], v[164:165]
	v_pk_mul_f32 v[166:167], v[64:65], v[166:167]
	v_pk_mul_f32 v[164:165], v[62:63], v[164:165]
	v_pk_fma_f32 v[170:171], v[64:65], v[156:157], v[170:171] neg_lo:[0,0,1] neg_hi:[0,0,1]
	v_pk_fma_f32 v[172:173], v[62:63], v[154:155], v[172:173] neg_lo:[0,0,1] neg_hi:[0,0,1]
	v_pk_fma_f32 v[156:157], v[60:61], v[156:157], v[166:167]
	v_pk_fma_f32 v[154:155], v[58:59], v[154:155], v[164:165]
	v_pk_mul_f32 v[156:157], v[156:157], s[38:39] op_sel_hi:[1,0]
	v_pk_mul_f32 v[154:155], v[154:155], s[38:39] op_sel_hi:[1,0]
	v_pk_mul_f32 v[170:171], v[170:171], s[38:39] op_sel_hi:[1,0]
	v_pk_mul_f32 v[172:173], v[172:173], s[38:39] op_sel_hi:[1,0]
	s_nop 0
	v_cvt_pk_bf16_f32 v164, v172, v173
	v_cvt_pk_bf16_f32 v165, v170, v171
	v_cvt_pk_bf16_f32 v154, v154, v155
	v_cvt_pk_bf16_f32 v155, v156, v157
	v_lshl_add_u64 v[156:157], s[24:25], 0, v[168:169]
	v_lshl_add_u64 v[156:157], v[156:157], 0, v[144:145]
	v_lshl_add_u64 v[166:167], v[156:157], 0, v[146:147]
	global_store_dwordx2 v[166:167], v[164:165], off
	global_store_dwordx2 v[166:167], v[154:155], off offset:64
	v_mov_b32_e32 v154, v178
	v_mov_b32_e32 v155, v179
	v_mov_b32_e32 v156, v180
	v_mov_b32_e32 v157, v181
	s_nop 0
	v_mov_b32_e32 v150, v182
	v_mov_b32_e32 v151, v183
	v_mov_b32_e32 v152, v184
	v_mov_b32_e32 v153, v185
	s_nop 0
	v_pk_mul_f32 v[168:169], v[50:51], v[150:151]
	v_pk_mul_f32 v[150:151], v[54:55], v[150:151]
	v_pk_mul_f32 v[164:165], v[52:53], v[152:153]
	v_pk_fma_f32 v[150:151], v[50:51], v[154:155], v[150:151]
	v_pk_fma_f32 v[164:165], v[56:57], v[156:157], v[164:165] neg_lo:[0,0,1] neg_hi:[0,0,1]
	v_pk_fma_f32 v[168:169], v[54:55], v[154:155], v[168:169] neg_lo:[0,0,1] neg_hi:[0,0,1]
	v_pk_mul_f32 v[152:153], v[56:57], v[152:153]
	v_pk_mul_f32 v[150:151], v[150:151], s[38:39] op_sel_hi:[1,0]
	v_pk_mul_f32 v[164:165], v[164:165], s[38:39] op_sel_hi:[1,0]
	v_pk_mul_f32 v[168:169], v[168:169], s[38:39] op_sel_hi:[1,0]
	v_pk_fma_f32 v[152:153], v[52:53], v[156:157], v[152:153]
	v_cvt_pk_bf16_f32 v154, v168, v169
	v_cvt_pk_bf16_f32 v155, v164, v165
	v_cvt_pk_bf16_f32 v150, v150, v151
	s_nop 0
	v_pk_mul_f32 v[152:153], v[152:153], s[38:39] op_sel_hi:[1,0]
	s_nop 0
	v_cvt_pk_bf16_f32 v151, v152, v153
	global_store_dwordx2 v[166:167], v[154:155], off offset:256
	global_store_dwordx2 v[166:167], v[150:151], off offset:320
	v_add_u32_e32 v150, 0x90, v142
	v_lshlrev_b32_e32 v143, 7, v150
	v_ashrrev_i32_e32 v151, 31, v150
	v_and_b32_e32 v152, 0x7ff80, v143
	v_mov_b32_e32 v153, v215
	v_lshlrev_b64 v[168:169], 10, v[150:151]
	v_lshl_add_u64 v[150:151], s[42:43], 0, v[152:153]
	v_lshl_add_u64 v[152:153], s[22:23], 0, v[152:153]
	v_lshl_add_u64 v[150:151], v[150:151], 0, v[148:149]
	v_lshl_add_u64 v[152:153], v[152:153], 0, v[148:149]
	global_load_dwordx4 v[154:157], v[150:151], off
	global_load_dwordx4 v[164:167], v[152:153], off
	s_waitcnt vmcnt(0)
; __device__ __forceinline__ unsigned cvt_pk_bf16(float lo, float hi) { unsigned r; asm volatile("v_cvt_pk_bf16_f32 %0, %1, %2" : "=v"(r) : "v"(lo), "v"(hi)); return r; }
; template <class V> __device__ __forceinline__ void st_wt8(void* p, const V v) { static_assert(sizeof(V) == 8, "8-byte value"); *(V*)p = v; }
; #define EPIIN_LOOP(...) _Pragma("unroll") for (int ai = 0; ai < 2; ++ai) _Pragma("unroll") for (int m = 0; m < 4; ++m) { const int row = row0 + ai * HALF + m * 16, t = row & (seq - 1); (void)t; \
;         _Pragma("unroll") for (int bj = 0; bj < 2; ++bj) { const int within = bj * HALF + wc * 32 + 8 * fq; const f32x4 v0 = acc[ai][bj][m][0], v1 = acc[ai][bj][m][1]; __VA_ARGS__ } }
;     __device__ __forceinline__ void operator()(const f32x4 (&acc)[2][2][4][2], const Unit& u, int wr, int wc, int fr, int fq) const {
;     ...
;         } else { const int hbase = (pn - 7) * 4;
;             EPIIN_LOOP({ const int hd = within >> 6, d = ((within & 63) >> 3) * 4; const f32x4 cc = *(const f32x4*)(rc + (size_t)t * 32 + d), ss = *(const f32x4*)(rs + (size_t)t * 32 + d);
;                 const f32x4 o1 = (v0 * cc - v1 * ss) * qscale, o2 = (v1 * cc + v0 * ss) * qscale;
;                 u32x2v w1, w2; w1.x = cvt_pk_bf16(o1[0], o1[1]); w1.y = cvt_pk_bf16(o1[2], o1[3]); w2.x = cvt_pk_bf16(o2[0], o2[1]); w2.y = cvt_pk_bf16(o2[2], o2[3]);
;                 bf16_t* dst = AQB + (size_t)row * 512 + (hbase + hd) * 64 + d; st_wt8(dst, w1); st_wt8(dst + 32, w2); })
	v_mov_b32_e32 v178, v154
	v_mov_b32_e32 v179, v155
	v_mov_b32_e32 v180, v156
	v_mov_b32_e32 v181, v157
	v_mov_b32_e32 v182, v164
	v_mov_b32_e32 v183, v165
	v_mov_b32_e32 v184, v166
	v_mov_b32_e32 v185, v167
	v_pk_mul_f32 v[170:171], v[44:45], v[166:167]
	v_pk_mul_f32 v[172:173], v[42:43], v[164:165]
	v_pk_mul_f32 v[166:167], v[48:49], v[166:167]
	v_pk_mul_f32 v[164:165], v[46:47], v[164:165]
	v_pk_fma_f32 v[170:171], v[48:49], v[156:157], v[170:171] neg_lo:[0,0,1] neg_hi:[0,0,1]
	v_pk_fma_f32 v[172:173], v[46:47], v[154:155], v[172:173] neg_lo:[0,0,1] neg_hi:[0,0,1]
	v_pk_fma_f32 v[156:157], v[44:45], v[156:157], v[166:167]
	v_pk_fma_f32 v[154:155], v[42:43], v[154:155], v[164:165]
	v_pk_mul_f32 v[156:157], v[156:157], s[38:39] op_sel_hi:[1,0]
	v_pk_mul_f32 v[154:155], v[154:155], s[38:39] op_sel_hi:[1,0]
	v_pk_mul_f32 v[170:171], v[170:171], s[38:39] op_sel_hi:[1,0]
	v_pk_mul_f32 v[172:173], v[172:173], s[38:39] op_sel_hi:[1,0]
	s_nop 0
	v_cvt_pk_bf16_f32 v164, v172, v173
	v_cvt_pk_bf16_f32 v165, v170, v171
	v_cvt_pk_bf16_f32 v154, v154, v155
	v_cvt_pk_bf16_f32 v155, v156, v157
	v_lshl_add_u64 v[156:157], s[24:25], 0, v[168:169]
	v_lshl_add_u64 v[156:157], v[156:157], 0, v[144:145]
	v_lshl_add_u64 v[166:167], v[156:157], 0, v[146:147]
	global_store_dwordx2 v[166:167], v[164:165], off
	global_store_dwordx2 v[166:167], v[154:155], off offset:64
	v_mov_b32_e32 v154, v178
	v_mov_b32_e32 v155, v179
	v_mov_b32_e32 v156, v180
	v_mov_b32_e32 v157, v181
	s_nop 0
	v_mov_b32_e32 v150, v182
	v_mov_b32_e32 v151, v183
	v_mov_b32_e32 v152, v184
	v_mov_b32_e32 v153, v185
	s_nop 0
	v_pk_mul_f32 v[168:169], v[34:35], v[150:151]
	v_pk_mul_f32 v[150:151], v[38:39], v[150:151]
	v_pk_mul_f32 v[164:165], v[36:37], v[152:153]
	v_pk_fma_f32 v[150:151], v[34:35], v[154:155], v[150:151]
	v_pk_fma_f32 v[164:165], v[40:41], v[156:157], v[164:165] neg_lo:[0,0,1] neg_hi:[0,0,1]
	v_pk_fma_f32 v[168:169], v[38:39], v[154:155], v[168:169] neg_lo:[0,0,1] neg_hi:[0,0,1]
	v_pk_mul_f32 v[152:153], v[40:41], v[152:153]
	v_pk_mul_f32 v[150:151], v[150:151], s[38:39] op_sel_hi:[1,0]
	v_pk_mul_f32 v[164:165], v[164:165], s[38:39] op_sel_hi:[1,0]
	v_pk_mul_f32 v[168:169], v[168:169], s[38:39] op_sel_hi:[1,0]
	v_pk_fma_f32 v[152:153], v[36:37], v[156:157], v[152:153]
	v_cvt_pk_bf16_f32 v154, v168, v169
	v_cvt_pk_bf16_f32 v155, v164, v165
	v_cvt_pk_bf16_f32 v150, v150, v151
	s_nop 0
	v_pk_mul_f32 v[152:153], v[152:153], s[38:39] op_sel_hi:[1,0]
	s_nop 0
	v_cvt_pk_bf16_f32 v151, v152, v153
	global_store_dwordx2 v[166:167], v[154:155], off offset:256
	global_store_dwordx2 v[166:167], v[150:151], off offset:320
	v_add_u32_e32 v150, 0xa0, v142
	v_lshlrev_b32_e32 v143, 7, v150
	v_ashrrev_i32_e32 v151, 31, v150
	v_and_b32_e32 v152, 0x7ff80, v143
	v_mov_b32_e32 v153, v215
	v_lshlrev_b64 v[168:169], 10, v[150:151]
	v_lshl_add_u64 v[150:151], s[42:43], 0, v[152:153]
	v_lshl_add_u64 v[152:153], s[22:23], 0, v[152:153]
	v_lshl_add_u64 v[150:151], v[150:151], 0, v[148:149]
	v_lshl_add_u64 v[152:153], v[152:153], 0, v[148:149]
	global_load_dwordx4 v[154:157], v[150:151], off
	global_load_dwordx4 v[164:167], v[152:153], off
	s_waitcnt vmcnt(0)
; __device__ __forceinline__ unsigned cvt_pk_bf16(float lo, float hi) { unsigned r; asm volatile("v_cvt_pk_bf16_f32 %0, %1, %2" : "=v"(r) : "v"(lo), "v"(hi)); return r; }
; template <class V> __device__ __forceinline__ void st_wt8(void* p, const V v) { static_assert(sizeof(V) == 8, "8-byte value"); *(V*)p = v; }
; #define EPIIN_LOOP(...) _Pragma("unroll") for (int ai = 0; ai < 2; ++ai) _Pragma("unroll") for (int m = 0; m < 4; ++m) { const int row = row0 + ai * HALF + m * 16, t = row & (seq - 1); (void)t; \
;         _Pragma("unroll") for (int bj = 0; bj < 2; ++bj) { const int within = bj * HALF + wc * 32 + 8 * fq; const f32x4 v0 = acc[ai][bj][m][0], v1 = acc[ai][bj][m][1]; __VA_ARGS__ } }
;     __device__ __forceinline__ void operator()(const f32x4 (&acc)[2][2][4][2], const Unit& u, int wr, int wc, int fr, int fq) const {
;     ...
;         } else { const int hbase = (pn - 7) * 4;
;             EPIIN_LOOP({ const int hd = within >> 6, d = ((within & 63) >> 3) * 4; const f32x4 cc = *(const f32x4*)(rc + (size_t)t * 32 + d), ss = *(const f32x4*)(rs + (size_t)t * 32 + d);
;                 const f32x4 o1 = (v0 * cc - v1 * ss) * qscale, o2 = (v1 * cc + v0 * ss) * qscale;
;                 u32x2v w1, w2; w1.x = cvt_pk_bf16(o1[0], o1[1]); w1.y = cvt_pk_bf16(o1[2], o1[3]); w2.x = cvt_pk_bf16(o2[0], o2[1]); w2.y = cvt_pk_bf16(o2[2], o2[3]);
;                 bf16_t* dst = AQB + (size_t)row * 512 + (hbase + hd) * 64 + d; st_wt8(dst, w1); st_wt8(dst + 32, w2); })
	v_mov_b32_e32 v178, v154
	v_mov_b32_e32 v179, v155
	v_mov_b32_e32 v180, v156
	v_mov_b32_e32 v181, v157
	v_mov_b32_e32 v182, v164
	v_mov_b32_e32 v183, v165
	v_mov_b32_e32 v184, v166
	v_mov_b32_e32 v185, v167
	v_pk_mul_f32 v[170:171], v[28:29], v[166:167]
	v_pk_mul_f32 v[172:173], v[26:27], v[164:165]
	v_pk_mul_f32 v[166:167], v[32:33], v[166:167]
	v_pk_mul_f32 v[164:165], v[30:31], v[164:165]
	v_pk_fma_f32 v[170:171], v[32:33], v[156:157], v[170:171] neg_lo:[0,0,1] neg_hi:[0,0,1]
	v_pk_fma_f32 v[172:173], v[30:31], v[154:155], v[172:173] neg_lo:[0,0,1] neg_hi:[0,0,1]
	v_pk_fma_f32 v[156:157], v[28:29], v[156:157], v[166:167]
	v_pk_fma_f32 v[154:155], v[26:27], v[154:155], v[164:165]
	v_pk_mul_f32 v[156:157], v[156:157], s[38:39] op_sel_hi:[1,0]
	v_pk_mul_f32 v[154:155], v[154:155], s[38:39] op_sel_hi:[1,0]
	v_pk_mul_f32 v[170:171], v[170:171], s[38:39] op_sel_hi:[1,0]
	v_pk_mul_f32 v[172:173], v[172:173], s[38:39] op_sel_hi:[1,0]
	s_nop 0
	v_cvt_pk_bf16_f32 v164, v172, v173
	v_cvt_pk_bf16_f32 v165, v170, v171
	v_cvt_pk_bf16_f32 v154, v154, v155
	v_cvt_pk_bf16_f32 v155, v156, v157
	v_lshl_add_u64 v[156:157], s[24:25], 0, v[168:169]
	v_lshl_add_u64 v[156:157], v[156:157], 0, v[144:145]
	v_lshl_add_u64 v[166:167], v[156:157], 0, v[146:147]
	global_store_dwordx2 v[166:167], v[164:165], off
	global_store_dwordx2 v[166:167], v[154:155], off offset:64
	v_mov_b32_e32 v154, v178
	v_mov_b32_e32 v155, v179
	v_mov_b32_e32 v156, v180
	v_mov_b32_e32 v157, v181
	s_nop 0
	v_mov_b32_e32 v150, v182
	v_mov_b32_e32 v151, v183
	v_mov_b32_e32 v152, v184
	v_mov_b32_e32 v153, v185
	s_nop 0
	v_pk_mul_f32 v[168:169], v[18:19], v[150:151]
	v_pk_mul_f32 v[150:151], v[22:23], v[150:151]
	v_pk_mul_f32 v[164:165], v[20:21], v[152:153]
	v_pk_fma_f32 v[150:151], v[18:19], v[154:155], v[150:151]
	v_pk_fma_f32 v[164:165], v[24:25], v[156:157], v[164:165] neg_lo:[0,0,1] neg_hi:[0,0,1]
	v_pk_fma_f32 v[168:169], v[22:23], v[154:155], v[168:169] neg_lo:[0,0,1] neg_hi:[0,0,1]
	v_pk_mul_f32 v[152:153], v[24:25], v[152:153]
	v_pk_mul_f32 v[150:151], v[150:151], s[38:39] op_sel_hi:[1,0]
	v_pk_mul_f32 v[164:165], v[164:165], s[38:39] op_sel_hi:[1,0]
	v_pk_mul_f32 v[168:169], v[168:169], s[38:39] op_sel_hi:[1,0]
	v_pk_fma_f32 v[152:153], v[20:21], v[156:157], v[152:153]
	v_cvt_pk_bf16_f32 v154, v168, v169
	v_cvt_pk_bf16_f32 v155, v164, v165
	v_cvt_pk_bf16_f32 v150, v150, v151
	v_mov_b32_e32 v165, v215
	v_pk_mul_f32 v[152:153], v[152:153], s[38:39] op_sel_hi:[1,0]
	s_nop 0
	v_cvt_pk_bf16_f32 v151, v152, v153
	global_store_dwordx2 v[166:167], v[154:155], off offset:256
	global_store_dwordx2 v[166:167], v[150:151], off offset:320
	v_add_u32_e32 v150, 0xb0, v142
	v_lshlrev_b32_e32 v143, 7, v150
	v_ashrrev_i32_e32 v151, 31, v150
	v_and_b32_e32 v164, 0x7ff80, v143
	v_lshlrev_b64 v[156:157], 10, v[150:151]
	v_lshl_add_u64 v[150:151], s[42:43], 0, v[164:165]
	v_lshl_add_u64 v[164:165], s[22:23], 0, v[164:165]
	v_lshl_add_u64 v[150:151], v[150:151], 0, v[148:149]
	v_lshl_add_u64 v[148:149], v[164:165], 0, v[148:149]
	global_load_dwordx4 v[152:155], v[150:151], off
	global_load_dwordx4 v[164:167], v[148:149], off
	v_readlane_b32 s42, v254, 41
	v_readlane_b32 s43, v254, 42
	s_waitcnt vmcnt(0)
	v_mov_b32_e32 v178, v152
	v_mov_b32_e32 v179, v153
	v_mov_b32_e32 v180, v154
	v_mov_b32_e32 v181, v155
	v_mov_b32_e32 v182, v164
	v_mov_b32_e32 v183, v165
	v_mov_b32_e32 v184, v166
	v_mov_b32_e32 v185, v167
	v_pk_mul_f32 v[168:169], v[12:13], v[166:167]
	v_pk_mul_f32 v[170:171], v[10:11], v[164:165]
	v_pk_mul_f32 v[166:167], v[16:17], v[166:167]
	v_pk_mul_f32 v[164:165], v[14:15], v[164:165]
	v_pk_fma_f32 v[168:169], v[16:17], v[154:155], v[168:169] neg_lo:[0,0,1] neg_hi:[0,0,1]
	v_pk_fma_f32 v[170:171], v[14:15], v[152:153], v[170:171] neg_lo:[0,0,1] neg_hi:[0,0,1]
	v_pk_fma_f32 v[154:155], v[12:13], v[154:155], v[166:167]
	v_pk_fma_f32 v[152:153], v[10:11], v[152:153], v[164:165]
	v_pk_mul_f32 v[154:155], v[154:155], s[38:39] op_sel_hi:[1,0]
	v_pk_mul_f32 v[152:153], v[152:153], s[38:39] op_sel_hi:[1,0]
	v_pk_mul_f32 v[168:169], v[168:169], s[38:39] op_sel_hi:[1,0]
	v_pk_mul_f32 v[170:171], v[170:171], s[38:39] op_sel_hi:[1,0]
	s_nop 0
	v_cvt_pk_bf16_f32 v164, v170, v171
	v_cvt_pk_bf16_f32 v165, v168, v169
	v_cvt_pk_bf16_f32 v152, v152, v153
	v_cvt_pk_bf16_f32 v153, v154, v155
	v_lshl_add_u64 v[154:155], s[24:25], 0, v[156:157]
	v_lshl_add_u64 v[144:145], v[154:155], 0, v[144:145]
	v_lshl_add_u64 v[154:155], v[144:145], 0, v[146:147]
	global_store_dwordx2 v[154:155], v[164:165], off
	global_store_dwordx2 v[154:155], v[152:153], off offset:64
	v_mov_b32_e32 v144, v178
	v_mov_b32_e32 v145, v179
	v_mov_b32_e32 v146, v180
	v_mov_b32_e32 v147, v181
	s_nop 0
	v_mov_b32_e32 v148, v182
	v_mov_b32_e32 v149, v183
	v_mov_b32_e32 v150, v184
	v_mov_b32_e32 v151, v185
	s_nop 0
	v_pk_mul_f32 v[152:153], v[4:5], v[150:151]
	v_pk_mul_f32 v[156:157], v[2:3], v[148:149]
	v_pk_mul_f32 v[148:149], v[6:7], v[148:149]
	v_pk_fma_f32 v[152:153], v[8:9], v[146:147], v[152:153] neg_lo:[0,0,1] neg_hi:[0,0,1]
	v_pk_fma_f32 v[156:157], v[6:7], v[144:145], v[156:157] neg_lo:[0,0,1] neg_hi:[0,0,1]
	v_pk_mul_f32 v[150:151], v[8:9], v[150:151]
	v_pk_fma_f32 v[144:145], v[2:3], v[144:145], v[148:149]
	v_pk_mul_f32 v[152:153], v[152:153], s[38:39] op_sel_hi:[1,0]
	v_pk_mul_f32 v[156:157], v[156:157], s[38:39] op_sel_hi:[1,0]
	v_pk_fma_f32 v[146:147], v[4:5], v[146:147], v[150:151]
	v_pk_mul_f32 v[144:145], v[144:145], s[38:39] op_sel_hi:[1,0]
	v_cvt_pk_bf16_f32 v148, v156, v157
	v_cvt_pk_bf16_f32 v149, v152, v153
	v_pk_mul_f32 v[146:147], v[146:147], s[38:39] op_sel_hi:[1,0]
	v_cvt_pk_bf16_f32 v144, v144, v145
	s_nop 0
	v_cvt_pk_bf16_f32 v145, v146, v147
	global_store_dwordx2 v[154:155], v[148:149], off offset:256
	global_store_dwordx2 v[154:155], v[144:145], off offset:320
	s_cbranch_execz .LBB0_310
	s_branch .LBB0_311

; #define LAS __attribute__((address_space(3)))
; __device__ __forceinline__ void idx_topk_phase(const IdxArgs& a, LAS unsigned char* lds_sc, LAS unsigned char* lds_scr, int G, int tid) {
;     const int lane = tid & 63, wave = __builtin_amdgcn_readfirstlane(tid >> 6), r = lane & 31, H = lane >> 5;
;     LAS float* SC = (LAS float*)lds_sc; LAS unsigned* scr = (LAS unsigned*)(lds_scr + wave * 1792);
;     constexpr int NJ = SEQ / 8, NU = BATCH * NJ;
;     ...
;     bf16x8 af[2][2], naf[2][2]; f32x4 wq[2][2][2], nwq[2][2][2]; int b, t0; bool ok;
;     IDX_UNIT(0, b, t0, ok);
;     if (ok) IDX_LOAD(af, wq, (size_t)b * SEQ + t0);
;     for (int i = 0; ok; ++i) {
;         { const int NT32 = (t0 + 8 + 31) >> 5;
;             { const bf16* kbase = a.KIB + ((size_t)b * SEQ + r) * 32 + 8 * H;
;               const int n = NT32 > wave ? (NT32 - wave + 7) >> 3 : 0;
.LBB0_720:
	s_or_b64 exec, exec, s[0:1]
	v_readlane_b32 s0, v251, 56
	v_readlane_b32 s1, v251, 57
	v_mov_b32_e32 v2, v0
	s_andn2_b64 vcc, exec, s[0:1]
	v_cndmask_b32_e64 v3, 0, 1, s[0:1]
	v_cmp_ne_u32_e64 s[2:3], 1, v3
	v_readfirstlane_b32 s0, v2
	s_nop 0
	v_writelane_b32 v254, s2, 58
	s_nop 1
	v_writelane_b32 v254, s3, 59
	s_cbranch_vccnz .LBB0_987
	v_bfe_u32 v10, v2, 5, 1
	v_lshlrev_b32_e32 v134, 1, v10
	v_readlane_b32 s1, v252, 1
	v_readlane_b32 s2, v252, 2
	v_and_b32_e32 v3, 3, v2
	v_or_b32_e32 v4, s1, v134
	v_mov_b32_e32 v5, s2
	v_lshrrev_b32_e32 v11, 1, v2
	v_lshlrev_b64 v[6:7], 5, v[4:5]
	v_readlane_b32 s2, v250, 25
	v_and_or_b32 v3, v11, 4, v3
	v_or_b32_e32 v8, 0xa0, v6
	v_mov_b32_e32 v9, v7
	v_readlane_b32 s3, v250, 26
	v_lshlrev_b32_e32 v214, 6, v3
	v_bfe_u32 v3, v2, 4, 1
	v_lshl_add_u64 v[8:9], s[2:3], 0, v[8:9]
	global_load_dwordx4 v[70:73], v[8:9], off offset:16
	global_load_dwordx4 v[78:81], v[8:9], off
	v_or_b32_e32 v8, 0x80, v6
	v_mov_b32_e32 v9, v7
	v_readlane_b32 s6, v250, 43
	v_and_or_b32 v138, v11, 2, v3
	v_lshl_add_u64 v[8:9], s[2:3], 0, v[8:9]
	v_readlane_b32 s7, v250, 44
	v_or_b32_e32 v4, s1, v138
	global_load_dwordx4 v[66:69], v[8:9], off offset:16
	global_load_dwordx4 v[74:77], v[8:9], off
	v_lshl_add_u64 v[8:9], s[6:7], 0, v[214:215]
	v_lshlrev_b32_e32 v214, 4, v10
	v_lshlrev_b64 v[4:5], 9, v[4:5]
	v_lshl_add_u64 v[136:137], v[8:9], 0, v[214:215]
	v_or_b32_e32 v8, 0x800, v4
	v_mov_b32_e32 v9, v5
	v_lshl_add_u64 v[8:9], v[136:137], 0, v[8:9]
	v_lshl_add_u64 v[6:7], s[2:3], 0, v[6:7]
	global_load_dwordx4 v[106:109], v[8:9], off offset:32
	global_load_dwordx4 v[110:113], v[8:9], off
	global_load_dwordx4 v[82:85], v[6:7], off offset:48
	global_load_dwordx4 v[86:89], v[6:7], off offset:32
	global_load_dwordx4 v[90:93], v[6:7], off offset:16
	global_load_dwordx4 v[94:97], v[6:7], off
	v_lshl_add_u64 v[4:5], v[136:137], 0, v[4:5]
	global_load_dwordx4 v[98:101], v[4:5], off offset:32
	global_load_dwordx4 v[102:105], v[4:5], off
	s_ashr_i32 s2, s0, 6
	s_mul_i32 s0, s2, 0x700
	s_add_i32 s88, s0, 0
	s_ashr_i32 s3, s2, 31
	s_add_i32 s10, s88, 0x20400
	s_lshl_b64 s[6:7], s[2:3], 11
	s_add_u32 s42, s6, 0x4000
	s_addc_u32 s43, s7, 0
	s_add_u32 s44, s6, 0x8000
	s_addc_u32 s45, s7, 0
	s_lshl_b32 s0, s2, 14
	v_and_b32_e32 v4, 31, v2
	s_add_i32 s3, s0, 0
	v_readlane_b32 s0, v250, 45
	v_and_b32_e32 v135, 63, v2
	v_lshlrev_b32_e32 v2, 6, v4
	v_mov_b32_e32 v3, v215
	v_readlane_b32 s1, v250, 46
	v_lshlrev_b32_e32 v139, 2, v135
	v_lshlrev_b32_e32 v152, 6, v135
	v_lshl_add_u64 v[2:3], s[0:1], 0, v[2:3]
	v_readlane_b32 s0, v251, 58
	v_lshl_add_u64 v[140:141], v[2:3], 0, v[214:215]
	v_lshlrev_b32_e32 v214, 15, v135
	v_readlane_b32 s1, v251, 59
	v_add_u32_e32 v146, s3, v139
	v_lshl_add_u32 v147, v135, 4, s10
	v_lshl_add_u64 v[142:143], s[0:1], 0, v[214:215]
	s_lshl_b32 s0, s2, 7
	v_lshl_add_u32 v2, v10, 15, s0
	v_lshl_or_b32 v2, v4, 2, v2
	s_add_i32 s0, 0, 0x10000
	s_mov_b32 s11, 0
	v_cmp_eq_u32_e64 s[12:13], 0, v135
	v_cmp_eq_u32_e64 s[14:15], 63, v135
	v_cmp_gt_u32_e64 s[16:17], 62, v135
	v_cmp_gt_u32_e64 s[18:19], 60, v135
	v_cmp_gt_u32_e64 s[20:21], 56, v135
	v_cmp_gt_u32_e64 s[22:23], 48, v135
	v_cmp_gt_u32_e64 s[24:25], 32, v135
	v_or_b32_e32 v148, 3, v139
	v_or_b32_e32 v149, 2, v139
	v_or_b32_e32 v150, 1, v139
	v_mul_i32_i24_e32 v151, -12, v135
	v_or_b32_e32 v153, 63, v152
	s_add_i32 s60, s2, 32
	v_add_u32_e32 v154, s0, v2
	s_add_i32 s88, s88, 0x20900
	v_readlane_b32 s48, v251, 62
	v_readlane_b32 s8, v252, 0
	v_readlane_b32 s49, v251, 63
	s_nop 3
	s_ashr_i32 s1, s48, 31
	s_mov_b32 s0, s48
	s_lshl_b64 s[0:1], s[0:1], 18
	v_lshl_add_u64 v[202:203], v[140:141], 0, s[0:1]
	v_lshl_add_u64 v[204:205], v[202:203], 0, s[6:7]
	global_load_dwordx4 v[186:189], v[204:205], off
	global_load_dwordx4 v[190:193], v[204:205], off offset:32
	v_lshl_add_u64 v[204:205], v[202:203], 0, s[42:43]
	global_load_dwordx4 v[194:197], v[204:205], off
	global_load_dwordx4 v[198:201], v[204:205], off offset:32
	s_branch .LBB0_723

; #define IDXP_MMA(C0, C1, B0, B1) { C0 = f32x16{}; C1 = f32x16{}; \
;                 C0 = __builtin_amdgcn_mfma_f32_32x32x16_bf16(af[0][0], B0, C0, 0, 0, 0); C1 = __builtin_amdgcn_mfma_f32_32x32x16_bf16(af[1][0], B0, C1, 0, 0, 0); \
;                 C0 = __builtin_amdgcn_mfma_f32_32x32x16_bf16(af[0][1], B1, C0, 0, 0, 0); C1 = __builtin_amdgcn_mfma_f32_32x32x16_bf16(af[1][1], B1, C1, 0, 0, 0); }
; __device__ __forceinline__ void idx_topk_phase(const IdxArgs& a, LAS unsigned char* lds_sc, LAS unsigned char* lds_scr, int G, int tid) {
;     ...
;         { const int NT32 = (t0 + 8 + 31) >> 5;
;             { const bf16* kbase = a.KIB + ((size_t)b * SEQ + r) * 32 + 8 * H;
;               const int n = NT32 > wave ? (NT32 - wave + 7) >> 3 : 0;
;     ...
;               bf16x8 bA0, bA1, bB0, bB1; f32x16 cA0, cA1, cB0, cB1;
;               if (n > 0) { IDXP_LD(bA0, bA1, 0); if (n > 1) IDXP_LD(bB0, bB1, 1);
;                   IDXP_MMA(cA0, cA1, bA0, bA1); if (n > 2) IDXP_LD(bA0, bA1, 2); }
.LBB0_723:
	s_add_i32 s0, s8, 39
	s_ashr_i32 s47, s48, 31
	s_mov_b32 s46, s48
	s_ashr_i32 s9, s0, 5
	s_lshl_b64 s[0:1], s[46:47], 18
	v_lshl_add_u64 v[130:131], v[140:141], 0, s[0:1]
	s_sub_i32 s0, s9, s2
	s_add_i32 s0, s0, 7
	s_lshr_b32 s0, s0, 3
	s_cmp_gt_i32 s9, s2
	s_cselect_b32 s9, s0, 0
	s_cmp_lg_u32 s9, 0
	s_cselect_b64 s[0:1], -1, 0
	s_cmp_eq_u32 s9, 0
	s_cbranch_scc1 .LBB0_728
	s_waitcnt vmcnt(0)
	v_mov_b32_e32 v114, v186
	v_mov_b32_e32 v115, v187
	v_mov_b32_e32 v116, v188
	v_mov_b32_e32 v117, v189
	v_mov_b32_e32 v126, v190
	v_mov_b32_e32 v127, v191
	v_mov_b32_e32 v128, v192
	v_mov_b32_e32 v129, v193
	s_cmp_eq_u32 s9, 1
	s_cbranch_scc1 .LBB0_726
	v_mov_b32_e32 v118, v194
	v_mov_b32_e32 v119, v195
	v_mov_b32_e32 v120, v196
	v_mov_b32_e32 v121, v197
	v_mov_b32_e32 v122, v198
	v_mov_b32_e32 v123, v199
	v_mov_b32_e32 v124, v200
	v_mov_b32_e32 v125, v201

; #define IDXP_MMA(C0, C1, B0, B1) { C0 = f32x16{}; C1 = f32x16{}; \
;                 C0 = __builtin_amdgcn_mfma_f32_32x32x16_bf16(af[0][0], B0, C0, 0, 0, 0); C1 = __builtin_amdgcn_mfma_f32_32x32x16_bf16(af[1][0], B0, C1, 0, 0, 0); \
;                 C0 = __builtin_amdgcn_mfma_f32_32x32x16_bf16(af[0][1], B1, C0, 0, 0, 0); C1 = __builtin_amdgcn_mfma_f32_32x32x16_bf16(af[1][1], B1, C1, 0, 0, 0); }
; __device__ __forceinline__ void idx_topk_phase(const IdxArgs& a, LAS unsigned char* lds_sc, LAS unsigned char* lds_scr, int G, int tid) {
;     ...
;               bf16x8 bA0, bA1, bB0, bB1; f32x16 cA0, cA1, cB0, cB1;
;               if (n > 0) { IDXP_LD(bA0, bA1, 0); if (n > 1) IDXP_LD(bB0, bB1, 1);
;                   IDXP_MMA(cA0, cA1, bA0, bA1); if (n > 2) IDXP_LD(bA0, bA1, 2); }
;               for (int j = 0; j < n; j += 2) {
;                   if (j + 1 < n) { IDXP_MMA(cB0, cB1, bB0, bB1); if (j + 3 < n) IDXP_LD(bB0, bB1, j + 3); }
;                   IDXP_EPI(cA0, cA1, j);
;                   if (j + 1 < n) {
;                       if (j + 2 < n) { IDXP_MMA(cA0, cA1, bA0, bA1); if (j + 4 < n) IDXP_LD(bA0, bA1, j + 4); }
;                       IDXP_EPI(cB0, cB1, j + 1); } }
.LBB0_730:
	s_add_i32 s1, s29, -3
	s_cmp_lt_u32 s1, s9
	s_cselect_b64 s[26:27], -1, 0
	s_cmp_ge_u32 s1, s9
	s_cbranch_scc1 .LBB0_733
	s_add_i32 s1, s29, -2
	s_cmp_lt_u32 s1, s9
	s_cbranch_scc1 .Lidx_w2a
	s_waitcnt vmcnt(0)
	s_branch .Lidx_g2a
.Lidx_w2a:
	s_waitcnt vmcnt(2)
.Lidx_g2a:
	v_mfma_f32_32x32x16_bf16 v[2:17], v[102:105], v[118:121], 0
	s_add_i32 s1, s29, -1
	s_cmp_ge_u32 s1, s9
	v_mfma_f32_32x32x16_bf16 v[18:33], v[110:113], v[118:121], 0
	v_mfma_f32_32x32x16_bf16 v[2:17], v[98:101], v[122:125], v[2:17]
	v_mfma_f32_32x32x16_bf16 v[18:33], v[106:109], v[122:125], v[18:33]
	s_cbranch_scc1 .LBB0_733
	s_add_i32 s30, s0, -8
	s_ashr_i32 s31, s30, 31
	s_lshl_b64 s[30:31], s[30:31], 11
	v_lshl_add_u64 v[122:123], v[130:131], 0, s[30:31]
	global_load_dwordx4 v[118:121], v[122:123], off
	s_nop 0
	global_load_dwordx4 v[122:125], v[122:123], off offset:32
.LBB0_733:
	v_med3_f32 v144, v34, 0, v242
	v_med3_f32 v145, v35, 0, v242
	v_pk_fma_f32 v[144:145], v[94:95], v[144:145], 0 op_sel_hi:[1,1,0]
	v_med3_f32 v158, v36, 0, v242
	v_med3_f32 v159, v37, 0, v242
	v_med3_f32 v156, v50, 0, v242
	v_med3_f32 v157, v51, 0, v242
	v_pk_fma_f32 v[144:145], v[96:97], v[158:159], v[144:145]
	v_med3_f32 v158, v38, 0, v242
	v_med3_f32 v159, v39, 0, v242
	v_pk_fma_f32 v[156:157], v[74:75], v[156:157], 0 op_sel_hi:[1,1,0]
	v_med3_f32 v160, v52, 0, v242
	v_med3_f32 v161, v53, 0, v242
	v_pk_fma_f32 v[144:145], v[90:91], v[158:159], v[144:145]
	v_med3_f32 v158, v40, 0, v242
	v_med3_f32 v159, v41, 0, v242
	v_pk_fma_f32 v[156:157], v[76:77], v[160:161], v[156:157]
	v_med3_f32 v160, v54, 0, v242
	v_med3_f32 v161, v55, 0, v242
	v_pk_fma_f32 v[144:145], v[92:93], v[158:159], v[144:145]
	v_pk_fma_f32 v[156:157], v[66:67], v[160:161], v[156:157]
	v_med3_f32 v160, v56, 0, v242
	v_med3_f32 v161, v57, 0, v242
	v_add_f32_e32 v133, v144, v145
	v_add_u32_e32 v144, 0xffff0000, v132
	v_pk_fma_f32 v[156:157], v[68:69], v[160:161], v[156:157]
	ds_write_b32 v144, v133
	v_med3_f32 v144, v42, 0, v242
	v_med3_f32 v145, v43, 0, v242
	v_add_f32_e32 v133, v156, v157
	v_med3_f32 v156, v58, 0, v242
	v_med3_f32 v157, v59, 0, v242
	v_pk_fma_f32 v[144:145], v[86:87], v[144:145], 0 op_sel_hi:[1,1,0]
	v_med3_f32 v158, v44, 0, v242
	v_med3_f32 v159, v45, 0, v242
	v_pk_fma_f32 v[156:157], v[78:79], v[156:157], 0 op_sel_hi:[1,1,0]
	v_med3_f32 v160, v60, 0, v242
	v_med3_f32 v161, v61, 0, v242
	v_pk_fma_f32 v[144:145], v[88:89], v[158:159], v[144:145]
	v_med3_f32 v158, v46, 0, v242
	v_med3_f32 v159, v47, 0, v242
	v_pk_fma_f32 v[156:157], v[80:81], v[160:161], v[156:157]
	v_med3_f32 v160, v62, 0, v242
	v_med3_f32 v161, v63, 0, v242
	v_pk_fma_f32 v[144:145], v[82:83], v[158:159], v[144:145]
	v_med3_f32 v158, v48, 0, v242
	v_med3_f32 v159, v49, 0, v242
	v_pk_fma_f32 v[156:157], v[70:71], v[160:161], v[156:157]
	v_med3_f32 v160, v64, 0, v242
	v_med3_f32 v161, v65, 0, v242
	v_pk_fma_f32 v[144:145], v[84:85], v[158:159], v[144:145]
	v_pk_fma_f32 v[156:157], v[72:73], v[160:161], v[156:157]
	v_add_f32_e32 v144, v144, v145
	v_add_u32_e32 v145, 0xffff4000, v132
	ds_write_b32 v145, v144
	v_add_f32_e32 v144, v156, v157
	s_andn2_b64 vcc, exec, s[26:27]
	ds_write2st64_b32 v132, v133, v144 offset1:64
	s_cbranch_vccnz .LBB0_738
	s_add_i32 s1, s29, -4
	s_cmp_ge_u32 s1, s28
	s_cbranch_scc1 .LBB0_737
	s_add_i32 s1, s29, -1
	s_cmp_lt_u32 s1, s9
	s_cbranch_scc1 .Lidx_w2b
	s_waitcnt vmcnt(0)
	s_branch .Lidx_g2b

; #define IDXP_MMA(C0, C1, B0, B1) { C0 = f32x16{}; C1 = f32x16{}; \
;                 C0 = __builtin_amdgcn_mfma_f32_32x32x16_bf16(af[0][0], B0, C0, 0, 0, 0); C1 = __builtin_amdgcn_mfma_f32_32x32x16_bf16(af[1][0], B0, C1, 0, 0, 0); \
;                 C0 = __builtin_amdgcn_mfma_f32_32x32x16_bf16(af[0][1], B1, C0, 0, 0, 0); C1 = __builtin_amdgcn_mfma_f32_32x32x16_bf16(af[1][1], B1, C1, 0, 0, 0); }
; __device__ __forceinline__ void idx_topk_phase(const IdxArgs& a, LAS unsigned char* lds_sc, LAS unsigned char* lds_scr, int G, int tid) {
;     ...
;               for (int j = 0; j < n; j += 2) {
;                   if (j + 1 < n) { IDXP_MMA(cB0, cB1, bB0, bB1); if (j + 3 < n) IDXP_LD(bB0, bB1, j + 3); }
;                   IDXP_EPI(cA0, cA1, j);
;                   if (j + 1 < n) {
;                       if (j + 2 < n) { IDXP_MMA(cA0, cA1, bA0, bA1); if (j + 4 < n) IDXP_LD(bA0, bA1, j + 4); }
;                       IDXP_EPI(cB0, cB1, j + 1); } }
.Lidx_g2b:
	v_mfma_f32_32x32x16_bf16 v[34:49], v[102:105], v[114:117], 0
	s_cmp_ge_u32 s29, s9
	v_mfma_f32_32x32x16_bf16 v[50:65], v[110:113], v[114:117], 0
	v_mfma_f32_32x32x16_bf16 v[34:49], v[98:101], v[126:129], v[34:49]
	v_mfma_f32_32x32x16_bf16 v[50:65], v[106:109], v[126:129], v[50:65]
	s_cbranch_scc1 .LBB0_737
	s_ashr_i32 s1, s0, 31
	s_lshl_b64 s[26:27], s[0:1], 11
	v_lshl_add_u64 v[126:127], v[130:131], 0, s[26:27]
	global_load_dwordx4 v[114:117], v[126:127], off
	s_nop 0
	global_load_dwordx4 v[126:129], v[126:127], off offset:32

; __device__ __forceinline__ void idx_topk_phase(const IdxArgs& a, LAS unsigned char* lds_sc, LAS unsigned char* lds_scr, int G, int tid) {
;     ...
;     bf16x8 af[2][2], naf[2][2]; f32x4 wq[2][2][2], nwq[2][2][2]; int b, t0; bool ok;
;     IDX_UNIT(0, b, t0, ok);
;     if (ok) IDX_LOAD(af, wq, (size_t)b * SEQ + t0);
;     for (int i = 0; ok; ++i) {
;         { const int NT32 = (t0 + 8 + 31) >> 5;
;             { const bf16* kbase = a.KIB + ((size_t)b * SEQ + r) * 32 + 8 * H;
;               const int n = NT32 > wave ? (NT32 - wave + 7) >> 3 : 0;
;     ...
;             int nb_, nt0_; bool nok_; IDX_UNIT(i + 1, nb_, nt0_, nok_);
;             if (nok_) IDX_LOAD(naf, nwq, (size_t)nb_ * SEQ + nt0_);
.LBB0_740:
	s_add_i32 s11, s11, 1
	s_lshr_b32 s0, s11, 3
	s_mul_i32 s0, s0, s68
	v_readlane_b32 s26, v249, 22
	s_add_i32 s0, s0, s26
	s_lshl_b32 s0, s0, 3
	s_and_b32 s1, s11, 7
	s_or_b32 s1, s0, s1
	s_cmpk_gt_i32 s0, 0x7ff
	s_cselect_b64 s[50:51], -1, 0
	s_ashr_i32 s9, s1, 31
	s_lshr_b32 s9, s9, 23
	s_add_i32 s9, s1, s9
	s_ashr_i32 s48, s9, 9
	s_and_b32 s9, s9, 0xfffffe00
	s_sub_i32 s1, s1, s9
	s_and_b32 s9, s1, 1
	s_ashr_i32 s1, s1, 1
	s_sub_i32 s26, 0x1ff, s1
	s_cmp_eq_u32 s9, 0
	s_cselect_b32 s1, s1, s26
	s_lshl_b32 s96, s1, 3
	s_cmpk_lt_i32 s0, 0x800
	v_readlane_b32 s27, v249, 23
	s_cbranch_scc0 .LBB0_742
	s_ashr_i32 s49, s48, 31
	s_lshl_b64 s[0:1], s[48:49], 12
	s_ashr_i32 s9, s96, 31
	s_add_u32 s0, s0, s96
	s_addc_u32 s1, s1, s9
	s_waitcnt vmcnt(4)
	v_mov_b32_e32 v67, s1
	v_or_b32_e32 v66, s0, v138
	v_mov_b32_e32 v69, s1
	v_or_b32_e32 v68, s0, v134
	v_readlane_b32 s0, v250, 25
	v_lshlrev_b64 v[66:67], 9, v[66:67]
	s_waitcnt vmcnt(2)
	v_lshlrev_b64 v[70:71], 5, v[68:69]
	v_readlane_b32 s1, v250, 26
	v_lshl_add_u64 v[66:67], v[136:137], 0, v[66:67]
	global_load_dwordx4 v[102:105], v[66:67], off
	global_load_dwordx4 v[98:101], v[66:67], off offset:32
	v_lshl_add_u64 v[68:69], s[0:1], 0, v[70:71]
	global_load_dwordx4 v[82:85], v[68:69], off offset:48
	global_load_dwordx4 v[86:89], v[68:69], off offset:32
	global_load_dwordx4 v[90:93], v[68:69], off offset:16
	global_load_dwordx4 v[94:97], v[68:69], off
	global_load_dwordx4 v[110:113], v[66:67], off offset:2048
	global_load_dwordx4 v[106:109], v[66:67], off offset:2080
	v_or_b32_e32 v66, 0x80, v70
	v_mov_b32_e32 v67, v71
	v_or_b32_e32 v70, 0xa0, v70
	v_lshl_add_u64 v[72:73], s[0:1], 0, v[66:67]
	s_waitcnt vmcnt(9)
	v_lshl_add_u64 v[78:79], s[0:1], 0, v[70:71]
	global_load_dwordx4 v[66:69], v[72:73], off offset:16
	global_load_dwordx4 v[74:77], v[72:73], off
	s_nop 0
	global_load_dwordx4 v[70:73], v[78:79], off offset:16
	s_nop 0
	global_load_dwordx4 v[78:81], v[78:79], off
	s_ashr_i32 s1, s48, 31
	s_mov_b32 s0, s48
	s_lshl_b64 s[0:1], s[0:1], 18
	v_lshl_add_u64 v[202:203], v[140:141], 0, s[0:1]
	v_lshl_add_u64 v[204:205], v[202:203], 0, s[6:7]
	global_load_dwordx4 v[186:189], v[204:205], off
	global_load_dwordx4 v[190:193], v[204:205], off offset:32
	v_lshl_add_u64 v[204:205], v[202:203], 0, s[42:43]
	global_load_dwordx4 v[194:197], v[204:205], off
	global_load_dwordx4 v[198:201], v[204:205], off offset:32
